# also GEMM4/GEMM5 second rounds split by rows between two workgroups (late weight conversion on workgroups 32+)
# speedup vs baseline: 1.0098x; 1.0098x over previous
.LBB0_1896:
	s_cmp_lt_i32 s50, 9
	s_cselect_b64 s[0:1], -1, 0
	s_and_b64 s[8:9], s[0:1], s[4:5]
	s_andn2_b64 vcc, exec, s[8:9]
	s_waitcnt vmcnt(0) lgkmcnt(0)
	v_bfe_u32 v1, v178, 2, 4
	s_cbranch_vccnz .LBB0_1915
	s_mov_b32 s101, 0
	v_readfirstlane_b32 s99, v179
	s_lshr_b32 s99, s99, 2
	s_cmpk_gt_i32 s2, 0x10f
	v_readfirstlane_b32 s0, v178
	s_barrier
	s_cbranch_scc1 .LBB0_1915
	v_lshrrev_b32_e32 v4, 3, v178
	s_movk_i32 s1, 0x70
	v_lshlrev_b32_e32 v2, 4, v178
	v_and_or_b32 v5, v4, s1, v1
	v_mul_u32_u24_e32 v10, 0x5200, v5
	v_add_u32_e32 v5, 0x2000, v2
	v_lshrrev_b32_e32 v5, 7, v5
	s_movk_i32 s1, 0xf0
	s_add_u32 s3, s46, 0x5201000
	v_and_or_b32 v6, v5, s1, v1
	s_addc_u32 s34, s47, 0
	v_lshrrev_b32_e32 v3, 2, v178
	v_mul_u32_u24_e32 v11, 0x5200, v6
	s_add_u32 s35, s46, 0x1a00000
	v_and_b32_e32 v6, 32, v178
	s_addc_u32 s36, s47, 0
	v_bitop3_b32 v12, v2, v6, 48 bitop3:0x6c
	v_lshlrev_b32_e32 v6, 1, v3
	v_lshrrev_b32_e32 v7, 5, v178
	s_ashr_i32 s38, s2, 31
	v_and_b32_e32 v6, 24, v6
	v_and_b32_e32 v7, 4, v7
	v_and_b32_e32 v3, 3, v3
	s_lshr_b32 s4, s38, 29
	v_or3_b32 v3, v7, v3, v6
	s_movk_i32 s1, 0x60
	s_add_i32 s4, s2, s4
	v_and_or_b32 v4, v4, s1, v3
	s_movk_i32 s1, 0xe0
	s_lshr_b32 s5, s0, 6
	s_ashr_i32 s6, s4, 3
	s_and_b32 s4, s4, -8
	v_and_or_b32 v3, v5, s1, v3
	s_lshr_b32 s1, s0, 8
	s_lshl_b32 s37, s5, 10
	s_sub_i32 s4, s2, s4
	s_cmp_lt_i32 s4, 0
	s_cselect_b32 s7, 35, 34
	s_mul_i32 s4, s4, s7
	s_add_i32 s4, s4, s6
	s_ashr_i32 s6, s4, 31
	s_lshr_b32 s6, s6, 27
	s_add_i32 s6, s4, s6
	s_ashr_i32 s6, s6, 5
	s_lshl_b32 s10, s6, 3
	s_sub_i32 s7, 0x44, s10
	s_lshl_b32 s6, s6, 5
	v_and_b32_e32 v13, 64, v178
	s_min_u32 s11, s7, 8
	s_sub_i32 s12, s4, s6
	v_or_b32_e32 v2, v12, v13
	s_sext_i32_i8 s4, s12
	v_cvt_f32_ubyte0_e32 v5, s11
	v_lshl_or_b32 v156, v4, 11, v2
	v_cvt_f32_i32_e32 v4, s4
	v_rcp_iflag_f32_e32 v6, v5
	v_or_b32_e32 v154, v2, v10
	v_or_b32_e32 v158, v11, v2
	v_lshl_or_b32 v160, v3, 11, v2
	v_mul_f32_e32 v2, v4, v6
	v_trunc_f32_e32 v2, v2
	v_fma_f32 v3, -v2, v5, v4
	v_cvt_i32_f32_e32 v2, v2
	s_ashr_i32 s4, s4, 30
	s_or_b32 s4, s4, 1
	v_cmp_ge_f32_e64 s[6:7], |v3|, v5
	s_and_b64 s[6:7], s[6:7], exec
	s_cselect_b32 s4, s4, 0
	v_readfirstlane_b32 s6, v2
	s_add_i32 s4, s6, s4
	s_mul_i32 s6, s4, s11
	s_sub_i32 s6, s12, s6
	s_sext_i32_i8 s6, s6
	s_add_i32 s64, s10, s6
	s_bfe_i64 s[6:7], s[4:5], 0x80000
	s_lshl_b64 s[6:7], s[6:7], 19
	s_add_u32 s28, s35, s6
	s_addc_u32 s29, s36, s7
	s_add_i32 s39, s37, 0
	s_add_i32 m0, s39, 0x10000
	s_mul_i32 s11, s64, 0x520000
	global_load_lds_dwordx4 v156, s[28:29]
	s_add_i32 m0, s39, 0x12000
	s_add_u32 s6, s28, 0x40000
	global_load_lds_dwordx4 v160, s[28:29]
	s_addc_u32 s7, s29, 0
	s_add_i32 m0, s39, 0x14000
	s_mul_hi_i32 s10, s64, 0x520000
	global_load_lds_dwordx4 v156, s[6:7]
	s_add_i32 m0, s39, 0x16000
	s_add_u32 s30, s3, s11
	s_addc_u32 s31, s34, s10
	s_add_i32 s40, s39, 0x2000
	global_load_lds_dwordx4 v160, s[6:7]
	s_mov_b32 m0, s39
	s_add_u32 s6, s30, 0x290000
	global_load_lds_dwordx4 v154, s[30:31]
	s_mov_b32 m0, s40
	s_addc_u32 s7, s31, 0
	s_add_i32 s41, s39, 0x4000
	global_load_lds_dwordx4 v158, s[30:31]
	s_mov_b32 m0, s41
	s_add_i32 s42, s39, 0x6000
	global_load_lds_dwordx4 v154, s[6:7]
	s_mov_b32 m0, s42
	v_mov_b32_e32 v157, 0
	global_load_lds_dwordx4 v158, s[6:7]
	v_mov_b32_e32 v161, v157
	v_mov_b32_e32 v155, v157
	v_mov_b32_e32 v159, v157
	s_cmp_eq_u32 s1, 1
	s_movk_i32 s43, 0x5200
	s_mov_b32 s56, 0
	v_lshl_add_u64 v[8:9], s[28:29], 0, v[156:157]
	v_lshl_add_u64 v[6:7], s[28:29], 0, v[160:161]
	v_lshl_add_u64 v[2:3], s[30:31], 0, v[154:155]
	s_cselect_b64 s[10:11], -1, 0
	s_cmp_lg_u32 s1, 1
	v_lshl_add_u64 v[4:5], s[30:31], 0, v[158:159]
	s_cbranch_scc1 .LBB0_1900
	s_barrier

.LBB0_1903:
	s_add_i32 s56, s56, 1
	s_mul_i32 s0, s56, s57
	s_mul_hi_u32 s1, s56, s60
	s_add_i32 s1, s1, s0
	s_mul_i32 s0, s56, s60
	s_add_u32 s4, s0, s2
	s_addc_u32 s5, s1, s38
	s_mov_b32 s100, s101
	s_mov_b32 s101, 0
	s_cmp_eq_u32 s48, 0x100
	s_cbranch_scc0 .Lsplit8_done
	s_cmp_eq_u32 s56, 1
	s_cbranch_scc0 .Lsplit8_done
	s_cmp_lt_u32 s2, 16
	s_cbranch_scc0 .Lsplit8_helper
	s_mov_b32 s101, 2
	s_branch .Lsplit8_done

.Lsplit8_done:
	s_sub_u32 s98, s100, 1
	v_cmp_gt_i64_e32 vcc, s[4:5], v[168:169]
	v_cmp_lt_i64_e64 s[6:7], s[4:5], v[166:167]
	s_cbranch_vccnz .LBB0_1905
	s_ashr_i32 s0, s4, 31
	s_lshr_b32 s0, s0, 29
	s_add_i32 s0, s4, s0
	s_ashr_i32 s1, s0, 3
	s_and_b32 s0, s0, -8
	s_sub_i32 s0, s4, s0
	s_cmp_lt_i32 s0, 0
	s_cselect_b32 s4, 35, 34
	s_mul_i32 s0, s0, s4
	s_add_i32 s0, s0, s1
	s_ashr_i32 s1, s0, 31
	s_lshr_b32 s1, s1, 27
	s_add_i32 s1, s0, s1
	s_ashr_i32 s4, s1, 5
	s_lshl_b32 s4, s4, 3
	s_sub_i32 s5, 0x44, s4
	s_min_i32 s5, s5, 8
	s_abs_i32 s22, s5
	v_cvt_f32_u32_e32 v2, s22
	s_sub_i32 s24, 0, s22
	s_andn2_b32 s1, s1, 31
	s_sub_i32 s0, s0, s1
	v_rcp_iflag_f32_e32 v2, v2
	s_abs_i32 s1, s0
	s_xor_b32 s23, s0, s5
	s_ashr_i32 s23, s23, 31
	v_mul_f32_e32 v2, 0x4f7ffffe, v2
	v_cvt_u32_f32_e32 v2, v2
	s_nop 0
	v_readfirstlane_b32 s25, v2
	s_mul_i32 s24, s24, s25
	s_mul_hi_u32 s24, s25, s24
	s_add_i32 s25, s25, s24
	s_mul_hi_u32 s24, s1, s25
	s_mul_i32 s25, s24, s22
	s_sub_i32 s1, s1, s25
	s_add_i32 s26, s24, 1
	s_sub_i32 s25, s1, s22
	s_cmp_ge_u32 s1, s22
	s_cselect_b32 s24, s26, s24
	s_cselect_b32 s1, s25, s1
	s_add_i32 s25, s24, 1
	s_cmp_ge_u32 s1, s22
	s_cselect_b32 s1, s25, s24
	s_xor_b32 s1, s1, s23
	s_sub_i32 s22, s1, s23
	s_mul_i32 s1, s22, s5
	s_sub_i32 s0, s0, s1
	s_add_i32 s63, s4, s0

.LBB0_1908:
	ds_read_b128 v[130:133], v187
	ds_read_b128 v[134:137], v187 offset:1024
	ds_read_b128 v[138:141], v187 offset:2048
	ds_read_b128 v[142:145], v187 offset:3072
	ds_read_b128 v[146:149], v188
	ds_read_b128 v[150:153], v188 offset:1024
	ds_read_b128 v[170:173], v188 offset:2048
	ds_read_b128 v[174:177], v188 offset:3072
	s_add_u32 s0, s6, 0xffd70080
	s_addc_u32 s1, s7, -1
	s_cmp_eq_u32 s69, 12
	s_cselect_b32 s31, s25, s1
	s_cselect_b32 s30, s24, s0
	s_cselect_b32 s29, s23, s68
	s_cselect_b32 s28, s66, s67
	v_lshl_add_u64 v[218:219], s[6:7], 0, v[162:163]
	s_add_i32 m0, s39, 0xc000
	ds_read_b128 v[180:183], v189
	ds_read_b128 v[190:193], v189 offset:1024
	ds_read_b128 v[194:197], v189 offset:2048
	ds_read_b128 v[198:201], v189 offset:3072
	ds_read_b128 v[202:205], v189 offset:4096
	ds_read_b128 v[206:209], v189 offset:5120
	ds_read_b128 v[210:213], v189 offset:6144
	ds_read_b128 v[214:217], v189 offset:7168
	global_load_lds_dwordx4 v[218:219], off
	v_lshl_add_u64 v[218:219], s[6:7], 0, v[164:165]
	s_add_i32 m0, s39, 0xe000
	s_nop 0
	global_load_lds_dwordx4 v[218:219], off
	s_waitcnt vmcnt(8)
	s_waitcnt lgkmcnt(0)
	s_barrier
	s_cmp_eq_u32 s99, s98
	s_cbranch_scc1 .Lsplit8_mma0
	s_setprio 1
	s_waitcnt lgkmcnt(0)
	v_mfma_f32_16x16x32_bf16 v[126:129], v[130:133], v[180:183], v[126:129]
	v_mfma_f32_16x16x32_bf16 v[122:125], v[138:141], v[180:183], v[122:125]
	v_mfma_f32_16x16x32_bf16 v[110:113], v[130:133], v[194:197], v[110:113]
	v_mfma_f32_16x16x32_bf16 v[106:109], v[138:141], v[194:197], v[106:109]
	v_mfma_f32_16x16x32_bf16 v[94:97], v[130:133], v[202:205], v[94:97]
	v_mfma_f32_16x16x32_bf16 v[90:93], v[138:141], v[202:205], v[90:93]
	v_mfma_f32_16x16x32_bf16 v[78:81], v[130:133], v[210:213], v[78:81]
	v_mfma_f32_16x16x32_bf16 v[74:77], v[138:141], v[210:213], v[74:77]
	v_mfma_f32_16x16x32_bf16 v[126:129], v[134:137], v[190:193], v[126:129]
	v_mfma_f32_16x16x32_bf16 v[122:125], v[142:145], v[190:193], v[122:125]
	v_mfma_f32_16x16x32_bf16 v[110:113], v[134:137], v[198:201], v[110:113]
	v_mfma_f32_16x16x32_bf16 v[106:109], v[142:145], v[198:201], v[106:109]
	v_mfma_f32_16x16x32_bf16 v[94:97], v[134:137], v[206:209], v[94:97]
	v_mfma_f32_16x16x32_bf16 v[90:93], v[142:145], v[206:209], v[90:93]
	v_mfma_f32_16x16x32_bf16 v[78:81], v[134:137], v[214:217], v[78:81]
	v_mfma_f32_16x16x32_bf16 v[74:77], v[142:145], v[214:217], v[74:77]
	s_setprio 0
	s_setprio 1
	v_mfma_f32_16x16x32_bf16 v[118:121], v[146:149], v[180:183], v[118:121]
	v_mfma_f32_16x16x32_bf16 v[114:117], v[170:173], v[180:183], v[114:117]
	v_mfma_f32_16x16x32_bf16 v[102:105], v[146:149], v[194:197], v[102:105]
	v_mfma_f32_16x16x32_bf16 v[98:101], v[170:173], v[194:197], v[98:101]
	v_mfma_f32_16x16x32_bf16 v[86:89], v[146:149], v[202:205], v[86:89]
	v_mfma_f32_16x16x32_bf16 v[82:85], v[170:173], v[202:205], v[82:85]
	v_mfma_f32_16x16x32_bf16 v[70:73], v[146:149], v[210:213], v[70:73]
	v_mfma_f32_16x16x32_bf16 v[66:69], v[170:173], v[210:213], v[66:69]
	v_mfma_f32_16x16x32_bf16 v[118:121], v[150:153], v[190:193], v[118:121]
	v_mfma_f32_16x16x32_bf16 v[114:117], v[174:177], v[190:193], v[114:117]
	v_mfma_f32_16x16x32_bf16 v[102:105], v[150:153], v[198:201], v[102:105]
	v_mfma_f32_16x16x32_bf16 v[98:101], v[174:177], v[198:201], v[98:101]
	v_mfma_f32_16x16x32_bf16 v[86:89], v[150:153], v[206:209], v[86:89]
	v_mfma_f32_16x16x32_bf16 v[82:85], v[174:177], v[206:209], v[82:85]
	v_mfma_f32_16x16x32_bf16 v[70:73], v[150:153], v[214:217], v[70:73]
	v_mfma_f32_16x16x32_bf16 v[66:69], v[174:177], v[214:217], v[66:69]
	s_setprio 0
.Lsplit8_mma0:
	s_barrier
	s_add_i32 s0, s61, s37
	v_lshl_add_u64 v[218:219], s[28:29], 0, v[156:157]
	s_mov_b32 m0, s0
	ds_read_b128 v[180:183], v189 offset:16384
	ds_read_b128 v[190:193], v189 offset:17408
	ds_read_b128 v[194:197], v189 offset:18432
	ds_read_b128 v[198:201], v189 offset:19456
	ds_read_b128 v[202:205], v189 offset:20480
	ds_read_b128 v[206:209], v189 offset:21504
	ds_read_b128 v[210:213], v189 offset:22528
	ds_read_b128 v[214:217], v189 offset:23552
	global_load_lds_dwordx4 v[218:219], off
	s_add_i32 m0, s0, 0x2000
	s_add_u32 s0, s28, 0x40000
	v_lshl_add_u64 v[220:221], s[28:29], 0, v[160:161]
	s_addc_u32 s1, s29, 0
	s_add_i32 s33, s62, s37
	global_load_lds_dwordx4 v[220:221], off
	v_lshl_add_u64 v[222:223], s[0:1], 0, v[156:157]
	s_mov_b32 m0, s33
	v_lshl_add_u64 v[224:225], s[30:31], 0, v[158:159]
	global_load_lds_dwordx4 v[222:223], off
	v_lshl_add_u64 v[222:223], s[0:1], 0, v[160:161]
	s_add_i32 m0, s33, 0x2000
	s_nop 0
	global_load_lds_dwordx4 v[222:223], off
	v_lshl_add_u64 v[222:223], s[30:31], 0, v[154:155]
	s_mov_b32 m0, s39
	s_nop 0
	global_load_lds_dwordx4 v[222:223], off
	s_mov_b32 m0, s40
	s_nop 0
	global_load_lds_dwordx4 v[224:225], off
	s_waitcnt vmcnt(8)
	s_waitcnt lgkmcnt(0)
	s_barrier
	s_cmp_eq_u32 s99, s98
	s_cbranch_scc1 .Lsplit8_mma1
	s_setprio 1
	s_waitcnt lgkmcnt(0)
	v_mfma_f32_16x16x32_bf16 v[62:65], v[130:133], v[180:183], v[62:65]
	v_mfma_f32_16x16x32_bf16 v[58:61], v[138:141], v[180:183], v[58:61]
	v_mfma_f32_16x16x32_bf16 v[46:49], v[130:133], v[194:197], v[46:49]
	v_mfma_f32_16x16x32_bf16 v[42:45], v[138:141], v[194:197], v[42:45]
	v_mfma_f32_16x16x32_bf16 v[30:33], v[130:133], v[202:205], v[30:33]
	v_mfma_f32_16x16x32_bf16 v[26:29], v[138:141], v[202:205], v[26:29]
	v_mfma_f32_16x16x32_bf16 v[14:17], v[130:133], v[210:213], v[14:17]
	v_mfma_f32_16x16x32_bf16 v[10:13], v[138:141], v[210:213], v[10:13]
	v_mfma_f32_16x16x32_bf16 v[62:65], v[134:137], v[190:193], v[62:65]
	v_mfma_f32_16x16x32_bf16 v[58:61], v[142:145], v[190:193], v[58:61]
	v_mfma_f32_16x16x32_bf16 v[46:49], v[134:137], v[198:201], v[46:49]
	v_mfma_f32_16x16x32_bf16 v[42:45], v[142:145], v[198:201], v[42:45]
	v_mfma_f32_16x16x32_bf16 v[30:33], v[134:137], v[206:209], v[30:33]
	v_mfma_f32_16x16x32_bf16 v[26:29], v[142:145], v[206:209], v[26:29]
	v_mfma_f32_16x16x32_bf16 v[14:17], v[134:137], v[214:217], v[14:17]
	v_mfma_f32_16x16x32_bf16 v[10:13], v[142:145], v[214:217], v[10:13]
	s_setprio 0
	s_setprio 1
	v_mfma_f32_16x16x32_bf16 v[54:57], v[146:149], v[180:183], v[54:57]
	v_mfma_f32_16x16x32_bf16 v[50:53], v[170:173], v[180:183], v[50:53]
	v_mfma_f32_16x16x32_bf16 v[38:41], v[146:149], v[194:197], v[38:41]
	v_mfma_f32_16x16x32_bf16 v[34:37], v[170:173], v[194:197], v[34:37]
	v_mfma_f32_16x16x32_bf16 v[22:25], v[146:149], v[202:205], v[22:25]
	v_mfma_f32_16x16x32_bf16 v[18:21], v[170:173], v[202:205], v[18:21]
	v_mfma_f32_16x16x32_bf16 v[6:9], v[146:149], v[210:213], v[6:9]
	v_mfma_f32_16x16x32_bf16 v[2:5], v[170:173], v[210:213], v[2:5]
	v_mfma_f32_16x16x32_bf16 v[54:57], v[150:153], v[190:193], v[54:57]
	v_mfma_f32_16x16x32_bf16 v[50:53], v[174:177], v[190:193], v[50:53]
	v_mfma_f32_16x16x32_bf16 v[38:41], v[150:153], v[198:201], v[38:41]
	v_mfma_f32_16x16x32_bf16 v[34:37], v[174:177], v[198:201], v[34:37]
	v_mfma_f32_16x16x32_bf16 v[22:25], v[150:153], v[206:209], v[22:25]
	v_mfma_f32_16x16x32_bf16 v[18:21], v[174:177], v[206:209], v[18:21]
	v_mfma_f32_16x16x32_bf16 v[6:9], v[150:153], v[214:217], v[6:9]
	v_mfma_f32_16x16x32_bf16 v[2:5], v[174:177], v[214:217], v[2:5]
	s_setprio 0
.Lsplit8_mma1:
	s_barrier
	s_add_i32 s33, 0, 0x18000
	s_add_i32 s52, 0, 0x1c000
	v_add_u32_e32 v142, s33, v185
	v_add_u32_e32 v174, s52, v185
	ds_read_b128 v[130:133], v142
	ds_read_b128 v[134:137], v142 offset:1024
	ds_read_b128 v[138:141], v142 offset:2048
	ds_read_b128 v[142:145], v142 offset:3072
	ds_read_b128 v[146:149], v174
	ds_read_b128 v[150:153], v174 offset:1024
	ds_read_b128 v[170:173], v174 offset:2048
	ds_read_b128 v[174:177], v174 offset:3072
	s_add_u32 s0, s30, 0x290000
	s_addc_u32 s1, s31, 0
	s_mov_b32 m0, s41
	v_lshl_add_u64 v[226:227], s[0:1], 0, v[154:155]
	ds_read_b128 v[180:183], v189 offset:32768
	ds_read_b128 v[190:193], v189 offset:33792
	ds_read_b128 v[194:197], v189 offset:34816
	ds_read_b128 v[198:201], v189 offset:35840
	ds_read_b128 v[202:205], v189 offset:36864
	ds_read_b128 v[206:209], v189 offset:37888
	ds_read_b128 v[210:213], v189 offset:38912
	ds_read_b128 v[214:217], v189 offset:39936
	global_load_lds_dwordx4 v[226:227], off
	v_lshl_add_u64 v[226:227], s[0:1], 0, v[158:159]
	s_mov_b32 m0, s42
	s_nop 0
	global_load_lds_dwordx4 v[226:227], off
	s_waitcnt vmcnt(8)
	s_waitcnt lgkmcnt(0)
	s_barrier
	s_cmp_eq_u32 s99, s98
	s_cbranch_scc1 .Lsplit8_mma2
	s_setprio 1
	s_waitcnt lgkmcnt(0)
	v_mfma_f32_16x16x32_bf16 v[126:129], v[130:133], v[180:183], v[126:129]
	v_mfma_f32_16x16x32_bf16 v[122:125], v[138:141], v[180:183], v[122:125]
	v_mfma_f32_16x16x32_bf16 v[110:113], v[130:133], v[194:197], v[110:113]
	v_mfma_f32_16x16x32_bf16 v[106:109], v[138:141], v[194:197], v[106:109]
	v_mfma_f32_16x16x32_bf16 v[94:97], v[130:133], v[202:205], v[94:97]
	v_mfma_f32_16x16x32_bf16 v[90:93], v[138:141], v[202:205], v[90:93]
	v_mfma_f32_16x16x32_bf16 v[78:81], v[130:133], v[210:213], v[78:81]
	v_mfma_f32_16x16x32_bf16 v[74:77], v[138:141], v[210:213], v[74:77]
	v_mfma_f32_16x16x32_bf16 v[126:129], v[134:137], v[190:193], v[126:129]
	v_mfma_f32_16x16x32_bf16 v[122:125], v[142:145], v[190:193], v[122:125]
	v_mfma_f32_16x16x32_bf16 v[110:113], v[134:137], v[198:201], v[110:113]
	v_mfma_f32_16x16x32_bf16 v[106:109], v[142:145], v[198:201], v[106:109]
	v_mfma_f32_16x16x32_bf16 v[94:97], v[134:137], v[206:209], v[94:97]
	v_mfma_f32_16x16x32_bf16 v[90:93], v[142:145], v[206:209], v[90:93]
	v_mfma_f32_16x16x32_bf16 v[78:81], v[134:137], v[214:217], v[78:81]
	v_mfma_f32_16x16x32_bf16 v[74:77], v[142:145], v[214:217], v[74:77]
	s_setprio 0
	s_setprio 1
	v_mfma_f32_16x16x32_bf16 v[118:121], v[146:149], v[180:183], v[118:121]
	v_mfma_f32_16x16x32_bf16 v[114:117], v[170:173], v[180:183], v[114:117]
	v_mfma_f32_16x16x32_bf16 v[102:105], v[146:149], v[194:197], v[102:105]
	v_mfma_f32_16x16x32_bf16 v[98:101], v[170:173], v[194:197], v[98:101]
	v_mfma_f32_16x16x32_bf16 v[86:89], v[146:149], v[202:205], v[86:89]
	v_mfma_f32_16x16x32_bf16 v[82:85], v[170:173], v[202:205], v[82:85]
	v_mfma_f32_16x16x32_bf16 v[70:73], v[146:149], v[210:213], v[70:73]
	v_mfma_f32_16x16x32_bf16 v[66:69], v[170:173], v[210:213], v[66:69]
	v_mfma_f32_16x16x32_bf16 v[118:121], v[150:153], v[190:193], v[118:121]
	v_mfma_f32_16x16x32_bf16 v[114:117], v[174:177], v[190:193], v[114:117]
	v_mfma_f32_16x16x32_bf16 v[102:105], v[150:153], v[198:201], v[102:105]
	v_mfma_f32_16x16x32_bf16 v[98:101], v[174:177], v[198:201], v[98:101]
	v_mfma_f32_16x16x32_bf16 v[86:89], v[150:153], v[206:209], v[86:89]
	v_mfma_f32_16x16x32_bf16 v[82:85], v[174:177], v[206:209], v[82:85]
	v_mfma_f32_16x16x32_bf16 v[70:73], v[150:153], v[214:217], v[70:73]
	v_mfma_f32_16x16x32_bf16 v[66:69], v[174:177], v[214:217], v[66:69]
	s_setprio 0
.Lsplit8_mma2:
	s_barrier
	s_add_i32 s0, s33, s37
	v_lshl_add_u64 v[218:219], v[218:219], 0, s[16:17]
	s_mov_b32 m0, s0
	ds_read_b128 v[180:183], v189 offset:49152
	ds_read_b128 v[190:193], v189 offset:50176
	ds_read_b128 v[194:197], v189 offset:51200
	ds_read_b128 v[198:201], v189 offset:52224
	ds_read_b128 v[202:205], v189 offset:53248
	ds_read_b128 v[206:209], v189 offset:54272
	ds_read_b128 v[210:213], v189 offset:55296
	ds_read_b128 v[214:217], v189 offset:56320
	global_load_lds_dwordx4 v[218:219], off
	s_add_i32 m0, s0, 0x2000
	s_add_u32 s0, s28, 0x40080
	v_lshl_add_u64 v[218:219], v[220:221], 0, s[16:17]
	s_addc_u32 s1, s29, 0
	s_add_i32 s28, s52, s37
	global_load_lds_dwordx4 v[218:219], off
	v_lshl_add_u64 v[218:219], s[0:1], 0, v[156:157]
	s_mov_b32 m0, s28
	s_nop 0
	global_load_lds_dwordx4 v[218:219], off
	v_lshl_add_u64 v[218:219], s[0:1], 0, v[160:161]
	s_add_i32 m0, s28, 0x2000
	s_nop 0
	global_load_lds_dwordx4 v[218:219], off
	v_lshl_add_u64 v[218:219], v[222:223], 0, s[16:17]
	s_mov_b32 m0, s58
	s_nop 0
	global_load_lds_dwordx4 v[218:219], off
	v_lshl_add_u64 v[218:219], v[224:225], 0, s[16:17]
	s_mov_b32 m0, s59
	s_nop 0
	global_load_lds_dwordx4 v[218:219], off
	s_waitcnt vmcnt(8)
	s_waitcnt lgkmcnt(0)
	s_barrier
	s_cmp_eq_u32 s99, s98
	s_cbranch_scc1 .Lsplit8_mma3
	s_setprio 1
	s_waitcnt lgkmcnt(0)
	v_mfma_f32_16x16x32_bf16 v[62:65], v[130:133], v[180:183], v[62:65]
	v_mfma_f32_16x16x32_bf16 v[58:61], v[138:141], v[180:183], v[58:61]
	v_mfma_f32_16x16x32_bf16 v[46:49], v[130:133], v[194:197], v[46:49]
	v_mfma_f32_16x16x32_bf16 v[42:45], v[138:141], v[194:197], v[42:45]
	v_mfma_f32_16x16x32_bf16 v[30:33], v[130:133], v[202:205], v[30:33]
	v_mfma_f32_16x16x32_bf16 v[26:29], v[138:141], v[202:205], v[26:29]
	v_mfma_f32_16x16x32_bf16 v[14:17], v[130:133], v[210:213], v[14:17]
	v_mfma_f32_16x16x32_bf16 v[10:13], v[138:141], v[210:213], v[10:13]
	v_mfma_f32_16x16x32_bf16 v[62:65], v[134:137], v[190:193], v[62:65]
	v_mfma_f32_16x16x32_bf16 v[58:61], v[142:145], v[190:193], v[58:61]
	v_mfma_f32_16x16x32_bf16 v[46:49], v[134:137], v[198:201], v[46:49]
	v_mfma_f32_16x16x32_bf16 v[42:45], v[142:145], v[198:201], v[42:45]
	v_mfma_f32_16x16x32_bf16 v[30:33], v[134:137], v[206:209], v[30:33]
	v_mfma_f32_16x16x32_bf16 v[26:29], v[142:145], v[206:209], v[26:29]
	v_mfma_f32_16x16x32_bf16 v[14:17], v[134:137], v[214:217], v[14:17]
	v_mfma_f32_16x16x32_bf16 v[10:13], v[142:145], v[214:217], v[10:13]
	s_setprio 0
	s_setprio 1
	v_mfma_f32_16x16x32_bf16 v[54:57], v[146:149], v[180:183], v[54:57]
	v_mfma_f32_16x16x32_bf16 v[50:53], v[170:173], v[180:183], v[50:53]
	v_mfma_f32_16x16x32_bf16 v[38:41], v[146:149], v[194:197], v[38:41]
	v_mfma_f32_16x16x32_bf16 v[34:37], v[170:173], v[194:197], v[34:37]
	v_mfma_f32_16x16x32_bf16 v[22:25], v[146:149], v[202:205], v[22:25]
	v_mfma_f32_16x16x32_bf16 v[18:21], v[170:173], v[202:205], v[18:21]
	v_mfma_f32_16x16x32_bf16 v[6:9], v[146:149], v[210:213], v[6:9]
	v_mfma_f32_16x16x32_bf16 v[2:5], v[170:173], v[210:213], v[2:5]
	v_mfma_f32_16x16x32_bf16 v[54:57], v[150:153], v[190:193], v[54:57]
	v_mfma_f32_16x16x32_bf16 v[50:53], v[174:177], v[190:193], v[50:53]
	v_mfma_f32_16x16x32_bf16 v[38:41], v[150:153], v[198:201], v[38:41]
	v_mfma_f32_16x16x32_bf16 v[34:37], v[174:177], v[198:201], v[34:37]
	v_mfma_f32_16x16x32_bf16 v[22:25], v[150:153], v[206:209], v[22:25]
	v_mfma_f32_16x16x32_bf16 v[18:21], v[174:177], v[206:209], v[18:21]
	v_mfma_f32_16x16x32_bf16 v[6:9], v[150:153], v[214:217], v[6:9]
	v_mfma_f32_16x16x32_bf16 v[2:5], v[174:177], v[214:217], v[2:5]
	s_setprio 0
.Lsplit8_mma3:
	s_barrier
	s_add_i32 s69, s69, 2
	s_add_u32 s6, s6, 0x100
	s_addc_u32 s7, s7, 0
	s_add_u32 s67, s67, 0x100
	s_addc_u32 s68, s68, 0
	s_cmp_gt_u32 s69, 13
	s_cbranch_scc0 .LBB0_1908
	s_and_b64 vcc, exec, s[18:19]
	s_cbranch_vccz .LBB0_1911
	s_barrier
.LBB0_1911:
	s_cmp_eq_u32 s99, s98
	s_cbranch_scc0 .Lsplit8_run
	s_and_b64 vcc, exec, s[4:5]
	s_mov_b64 s[4:5], -1
	s_branch .Lsplit8_epi
.Lsplit8_run:
	v_lshl_add_u32 v172, s64, 8, v184
	v_lshl_or_b32 v130, s65, 8, v186
	v_mov_b64_e32 v[174:175], s[46:47]
	v_ashrrev_i32_e32 v131, 31, v130
	v_mad_i64_i32 v[132:133], s[0:1], v172, s43, v[174:175]
	v_lshl_add_u64 v[132:133], v[132:133], 0, s[20:21]
	v_lshlrev_b64 v[170:171], 1, v[130:131]
	v_lshl_add_u64 v[134:135], v[132:133], 0, v[170:171]
	v_ashrrev_i32_e32 v173, 31, v172
	v_or_b32_e32 v130, 0x80, v130
	global_load_dwordx4 v[190:193], v[134:135], off
	v_lshlrev_b64 v[134:135], 11, v[172:173]
	v_ashrrev_i32_e32 v131, 31, v130
	v_lshl_add_u64 v[136:137], s[12:13], 0, v[134:135]
	v_lshlrev_b64 v[176:177], 1, v[130:131]
	v_lshl_add_u64 v[136:137], v[136:137], 0, v[170:171]
	v_lshl_add_u64 v[130:131], v[132:133], 0, v[176:177]
	global_load_dwordx4 v[194:197], v[136:137], off
	global_load_dwordx4 v[198:201], v[130:131], off
	global_load_dwordx4 v[202:205], v[136:137], off offset:256
	v_or_b32_e32 v130, 16, v172
	v_or_b32_e32 v136, 48, v172
	v_ashrrev_i32_e32 v131, 31, v130
	v_mad_i64_i32 v[138:139], s[0:1], v130, s43, v[174:175]
	v_ashrrev_i32_e32 v137, 31, v136
	v_lshlrev_b64 v[230:231], 11, v[130:131]
	v_mad_i64_i32 v[142:143], s[0:1], v136, s43, v[174:175]
	v_lshl_add_u64 v[138:139], v[138:139], 0, s[20:21]
	v_lshlrev_b64 v[180:181], 11, v[136:137]
	v_lshl_add_u64 v[136:137], s[12:13], 0, v[230:231]
	v_lshl_add_u64 v[144:145], v[138:139], 0, v[170:171]
	v_lshl_add_u64 v[136:137], v[136:137], 0, v[170:171]
	global_load_dwordx4 v[206:209], v[144:145], off
	global_load_dwordx4 v[210:213], v[136:137], off
	v_or_b32_e32 v132, 32, v172
	v_ashrrev_i32_e32 v133, 31, v132
	v_mad_i64_i32 v[140:141], s[0:1], v132, s43, v[174:175]
	v_lshlrev_b64 v[182:183], 11, v[132:133]
	v_lshl_add_u64 v[130:131], v[140:141], 0, s[20:21]
	v_lshl_add_u64 v[132:133], v[142:143], 0, s[20:21]
	v_lshl_add_u64 v[134:135], s[14:15], 0, v[134:135]
	v_lshl_add_u64 v[140:141], s[12:13], 0, v[182:183]
	v_lshl_add_u64 v[138:139], v[138:139], 0, v[176:177]
	v_lshl_add_u64 v[142:143], v[130:131], 0, v[170:171]
	v_lshl_add_u64 v[130:131], v[130:131], 0, v[176:177]
	v_lshl_add_u64 v[144:145], s[12:13], 0, v[180:181]
	v_lshl_add_u64 v[234:235], v[132:133], 0, v[170:171]
	v_lshl_add_u64 v[132:133], v[132:133], 0, v[176:177]
	v_lshl_add_u64 v[236:237], v[134:135], 0, v[170:171]
	v_lshl_add_u64 v[134:135], v[140:141], 0, v[170:171]
	v_lshl_add_u64 v[238:239], v[144:145], 0, v[170:171]
	global_load_dwordx4 v[214:217], v[138:139], off
	global_load_dwordx4 v[218:221], v[136:137], off offset:256
	global_load_dwordx4 v[222:225], v[142:143], off
	global_load_dwordx4 v[226:229], v[134:135], off
	global_load_dwordx4 v[150:153], v[130:131], off
	global_load_dwordx4 v[146:149], v[134:135], off offset:256
	s_nop 0
	global_load_dwordx4 v[142:145], v[234:235], off
	global_load_dwordx4 v[138:141], v[238:239], off
	global_load_dwordx4 v[134:137], v[132:133], off
	s_nop 0
	global_load_dwordx4 v[130:133], v[238:239], off offset:256
	s_and_b64 vcc, exec, s[4:5]
	s_mov_b64 s[4:5], -1
	s_waitcnt vmcnt(0)
	v_lshlrev_b32_e32 v234, 16, v190
	v_and_b32_e32 v235, 0xffff0000, v190
	v_lshlrev_b32_e32 v190, 16, v191
	v_and_b32_e32 v191, 0xffff0000, v191
	v_lshlrev_b32_e32 v238, 16, v192
	v_and_b32_e32 v239, 0xffff0000, v192
	v_lshlrev_b32_e32 v192, 16, v193
	v_and_b32_e32 v193, 0xffff0000, v193
	v_lshlrev_b32_e32 v240, 16, v194
	v_and_b32_e32 v241, 0xffff0000, v194
	v_lshlrev_b32_e32 v194, 16, v195
	v_and_b32_e32 v195, 0xffff0000, v195
	v_lshlrev_b32_e32 v242, 16, v196
	v_and_b32_e32 v243, 0xffff0000, v196
	v_lshlrev_b32_e32 v196, 16, v197
	v_and_b32_e32 v197, 0xffff0000, v197
	v_pk_fma_f32 v[128:129], v[128:129], v[190:191], v[194:195]
	v_pk_fma_f32 v[126:127], v[126:127], v[234:235], v[240:241]
	v_pk_fma_f32 v[190:191], v[124:125], v[192:193], v[196:197]
	v_pk_fma_f32 v[124:125], v[122:123], v[238:239], v[242:243]
	v_cvt_pk_bf16_f32 v122, v126, v127
	v_cvt_pk_bf16_f32 v123, v128, v129
	v_lshlrev_b32_e32 v126, 16, v200
	v_cvt_pk_bf16_f32 v124, v124, v125
	v_cvt_pk_bf16_f32 v125, v190, v191
	global_store_dwordx4 v[236:237], v[122:125], off
	v_and_b32_e32 v127, 0xffff0000, v200
	v_lshlrev_b32_e32 v128, 16, v201
	v_lshlrev_b32_e32 v122, 16, v198
	v_and_b32_e32 v123, 0xffff0000, v198
	v_and_b32_e32 v129, 0xffff0000, v201
	v_lshlrev_b32_e32 v190, 16, v202
	v_and_b32_e32 v191, 0xffff0000, v202
	v_lshlrev_b32_e32 v194, 16, v204
	v_and_b32_e32 v195, 0xffff0000, v204
	v_lshlrev_b32_e32 v196, 16, v205
	v_and_b32_e32 v197, 0xffff0000, v205
	v_lshlrev_b32_e32 v124, 16, v199
	v_and_b32_e32 v125, 0xffff0000, v199
	v_lshlrev_b32_e32 v192, 16, v203
	v_and_b32_e32 v193, 0xffff0000, v203
	v_pk_fma_f32 v[118:119], v[118:119], v[122:123], v[190:191]
	v_pk_fma_f32 v[122:123], v[116:117], v[128:129], v[196:197]
	v_pk_fma_f32 v[116:117], v[114:115], v[126:127], v[194:195]
	v_pk_fma_f32 v[120:121], v[120:121], v[124:125], v[192:193]
	v_cvt_pk_bf16_f32 v114, v118, v119
	v_cvt_pk_bf16_f32 v116, v116, v117
	v_cvt_pk_bf16_f32 v117, v122, v123
	v_lshlrev_b32_e32 v118, 16, v208
	v_cvt_pk_bf16_f32 v115, v120, v121
	global_store_dwordx4 v[236:237], v[114:117], off offset:256
	v_and_b32_e32 v119, 0xffff0000, v208
	v_lshlrev_b32_e32 v120, 16, v209
	v_lshlrev_b32_e32 v114, 16, v206
	v_and_b32_e32 v115, 0xffff0000, v206
	v_lshlrev_b32_e32 v116, 16, v207
	v_and_b32_e32 v117, 0xffff0000, v207
	v_and_b32_e32 v121, 0xffff0000, v209
	v_lshlrev_b32_e32 v122, 16, v210
	v_and_b32_e32 v123, 0xffff0000, v210
	v_lshlrev_b32_e32 v124, 16, v211
	v_and_b32_e32 v125, 0xffff0000, v211
	v_lshlrev_b32_e32 v126, 16, v212
	v_and_b32_e32 v127, 0xffff0000, v212
	v_lshlrev_b32_e32 v128, 16, v213
	v_and_b32_e32 v129, 0xffff0000, v213
	v_lshl_add_u64 v[190:191], s[14:15], 0, v[230:231]
	v_lshl_add_u64 v[190:191], v[190:191], 0, v[170:171]
	v_pk_fma_f32 v[112:113], v[112:113], v[116:117], v[124:125]
	v_pk_fma_f32 v[110:111], v[110:111], v[114:115], v[122:123]
	v_pk_fma_f32 v[114:115], v[108:109], v[120:121], v[128:129]
	v_pk_fma_f32 v[108:109], v[106:107], v[118:119], v[126:127]
	v_cvt_pk_bf16_f32 v106, v110, v111
	v_cvt_pk_bf16_f32 v107, v112, v113
	v_lshlrev_b32_e32 v110, 16, v216
	v_cvt_pk_bf16_f32 v108, v108, v109
	v_cvt_pk_bf16_f32 v109, v114, v115
	global_store_dwordx4 v[190:191], v[106:109], off
	v_and_b32_e32 v111, 0xffff0000, v216
	v_lshlrev_b32_e32 v112, 16, v217
	v_lshlrev_b32_e32 v106, 16, v214
	v_and_b32_e32 v107, 0xffff0000, v214
	v_and_b32_e32 v113, 0xffff0000, v217
	v_lshlrev_b32_e32 v114, 16, v218
	v_and_b32_e32 v115, 0xffff0000, v218
	v_lshlrev_b32_e32 v118, 16, v220
	v_and_b32_e32 v119, 0xffff0000, v220
	v_lshlrev_b32_e32 v120, 16, v221
	v_and_b32_e32 v121, 0xffff0000, v221
	v_lshlrev_b32_e32 v108, 16, v215
	v_and_b32_e32 v109, 0xffff0000, v215
	v_lshlrev_b32_e32 v116, 16, v219
	v_and_b32_e32 v117, 0xffff0000, v219
	v_pk_fma_f32 v[102:103], v[102:103], v[106:107], v[114:115]
	v_pk_fma_f32 v[106:107], v[100:101], v[112:113], v[120:121]
	v_pk_fma_f32 v[100:101], v[98:99], v[110:111], v[118:119]
	v_pk_fma_f32 v[104:105], v[104:105], v[108:109], v[116:117]
	v_cvt_pk_bf16_f32 v98, v102, v103
	v_cvt_pk_bf16_f32 v100, v100, v101
	v_cvt_pk_bf16_f32 v101, v106, v107
	v_lshlrev_b32_e32 v102, 16, v224
	v_cvt_pk_bf16_f32 v99, v104, v105
	global_store_dwordx4 v[190:191], v[98:101], off offset:256
	v_and_b32_e32 v103, 0xffff0000, v224
	v_lshlrev_b32_e32 v104, 16, v225
	v_lshlrev_b32_e32 v98, 16, v222
	v_and_b32_e32 v99, 0xffff0000, v222
	v_lshlrev_b32_e32 v100, 16, v223
	v_and_b32_e32 v101, 0xffff0000, v223
	v_and_b32_e32 v105, 0xffff0000, v225
	v_lshlrev_b32_e32 v106, 16, v226
	v_and_b32_e32 v107, 0xffff0000, v226
	v_lshlrev_b32_e32 v108, 16, v227
	v_and_b32_e32 v109, 0xffff0000, v227
	v_lshlrev_b32_e32 v110, 16, v228
	v_and_b32_e32 v111, 0xffff0000, v228
	v_lshlrev_b32_e32 v112, 16, v229
	v_and_b32_e32 v113, 0xffff0000, v229
	v_lshl_add_u64 v[114:115], s[14:15], 0, v[182:183]
	v_lshl_add_u64 v[114:115], v[114:115], 0, v[170:171]
	v_pk_fma_f32 v[96:97], v[96:97], v[100:101], v[108:109]
	v_pk_fma_f32 v[94:95], v[94:95], v[98:99], v[106:107]
	v_pk_fma_f32 v[98:99], v[92:93], v[104:105], v[112:113]
	v_pk_fma_f32 v[92:93], v[90:91], v[102:103], v[110:111]
	v_cvt_pk_bf16_f32 v90, v94, v95
	v_cvt_pk_bf16_f32 v91, v96, v97
	v_lshlrev_b32_e32 v94, 16, v152
	v_cvt_pk_bf16_f32 v92, v92, v93
	v_cvt_pk_bf16_f32 v93, v98, v99
	global_store_dwordx4 v[114:115], v[90:93], off
	v_and_b32_e32 v95, 0xffff0000, v152
	v_lshlrev_b32_e32 v96, 16, v153
	v_lshlrev_b32_e32 v90, 16, v150
	v_and_b32_e32 v91, 0xffff0000, v150
	v_and_b32_e32 v97, 0xffff0000, v153
	v_lshlrev_b32_e32 v98, 16, v146
	v_and_b32_e32 v99, 0xffff0000, v146
	v_lshlrev_b32_e32 v102, 16, v148
	v_and_b32_e32 v103, 0xffff0000, v148
	v_lshlrev_b32_e32 v104, 16, v149
	v_and_b32_e32 v105, 0xffff0000, v149
	v_pk_fma_f32 v[86:87], v[86:87], v[90:91], v[98:99]
	v_pk_fma_f32 v[90:91], v[84:85], v[96:97], v[104:105]
	v_pk_fma_f32 v[84:85], v[82:83], v[94:95], v[102:103]
	v_lshlrev_b32_e32 v92, 16, v151
	v_and_b32_e32 v93, 0xffff0000, v151
	v_lshlrev_b32_e32 v100, 16, v147
	v_and_b32_e32 v101, 0xffff0000, v147
	v_cvt_pk_bf16_f32 v84, v84, v85
	v_cvt_pk_bf16_f32 v85, v90, v91
	v_pk_fma_f32 v[88:89], v[88:89], v[92:93], v[100:101]
	v_cvt_pk_bf16_f32 v82, v86, v87
	v_lshlrev_b32_e32 v92, 16, v139
	v_cvt_pk_bf16_f32 v83, v88, v89
	global_store_dwordx4 v[114:115], v[82:85], off offset:256
	v_and_b32_e32 v93, 0xffff0000, v139
	v_lshlrev_b32_e32 v86, 16, v144
	v_lshlrev_b32_e32 v84, 16, v143
	v_and_b32_e32 v85, 0xffff0000, v143
	v_lshlrev_b32_e32 v82, 16, v142
	v_and_b32_e32 v83, 0xffff0000, v142
	v_and_b32_e32 v87, 0xffff0000, v144
	v_lshlrev_b32_e32 v88, 16, v145
	v_and_b32_e32 v89, 0xffff0000, v145
	v_lshlrev_b32_e32 v90, 16, v138
	v_and_b32_e32 v91, 0xffff0000, v138
	v_lshlrev_b32_e32 v94, 16, v140
	v_and_b32_e32 v95, 0xffff0000, v140
	v_lshlrev_b32_e32 v96, 16, v141
	v_and_b32_e32 v97, 0xffff0000, v141
	v_pk_fma_f32 v[80:81], v[80:81], v[84:85], v[92:93]
	v_lshl_add_u64 v[98:99], s[14:15], 0, v[180:181]
	v_pk_fma_f32 v[78:79], v[78:79], v[82:83], v[90:91]
	v_pk_fma_f32 v[82:83], v[76:77], v[88:89], v[96:97]
	v_pk_fma_f32 v[76:77], v[74:75], v[86:87], v[94:95]
	v_cvt_pk_bf16_f32 v75, v80, v81
	v_add_u32_e32 v80, 0x80, v172
	v_lshl_add_u64 v[98:99], v[98:99], 0, v[170:171]
	v_cvt_pk_bf16_f32 v74, v78, v79
	v_cvt_pk_bf16_f32 v76, v76, v77
	v_cvt_pk_bf16_f32 v77, v82, v83
	v_ashrrev_i32_e32 v81, 31, v80
	global_store_dwordx4 v[98:99], v[74:77], off
	v_mad_i64_i32 v[82:83], s[0:1], v80, s43, v[174:175]
	s_nop 0
	v_lshlrev_b32_e32 v74, 16, v134
	v_and_b32_e32 v75, 0xffff0000, v134
	v_lshlrev_b32_e32 v76, 16, v135
	v_and_b32_e32 v77, 0xffff0000, v135
	v_lshlrev_b64 v[134:135], 11, v[80:81]
	v_lshl_add_u64 v[82:83], v[82:83], 0, s[20:21]
	v_lshl_add_u64 v[80:81], s[12:13], 0, v[134:135]
	v_lshl_add_u64 v[84:85], v[82:83], 0, v[170:171]
	v_lshl_add_u64 v[80:81], v[80:81], 0, v[170:171]
	v_lshlrev_b32_e32 v78, 16, v136
	global_load_dwordx4 v[102:105], v[84:85], off
	global_load_dwordx4 v[106:109], v[80:81], off
	v_and_b32_e32 v79, 0xffff0000, v136
	v_lshlrev_b32_e32 v84, 16, v137
	v_and_b32_e32 v85, 0xffff0000, v137
	v_lshlrev_b32_e32 v86, 16, v130
	v_and_b32_e32 v87, 0xffff0000, v130
	v_lshlrev_b32_e32 v88, 16, v131
	v_and_b32_e32 v89, 0xffff0000, v131
	v_lshlrev_b32_e32 v90, 16, v132
	v_and_b32_e32 v91, 0xffff0000, v132
	v_lshlrev_b32_e32 v92, 16, v133
	v_and_b32_e32 v93, 0xffff0000, v133
	v_pk_fma_f32 v[72:73], v[72:73], v[76:77], v[88:89]
	v_pk_fma_f32 v[70:71], v[70:71], v[74:75], v[86:87]
	v_pk_fma_f32 v[74:75], v[68:69], v[84:85], v[92:93]
	v_pk_fma_f32 v[68:69], v[66:67], v[78:79], v[90:91]
	v_cvt_pk_bf16_f32 v66, v70, v71
	v_cvt_pk_bf16_f32 v67, v72, v73
	v_lshl_add_u64 v[134:135], s[14:15], 0, v[134:135]
	v_cvt_pk_bf16_f32 v68, v68, v69
	v_cvt_pk_bf16_f32 v69, v74, v75
	global_store_dwordx4 v[98:99], v[66:69], off offset:256
	v_lshl_add_u64 v[134:135], v[134:135], 0, v[170:171]
	s_waitcnt vmcnt(2)
	v_lshlrev_b32_e32 v138, 16, v102
	v_lshl_add_u64 v[66:67], v[82:83], 0, v[176:177]
	global_load_dwordx4 v[110:113], v[66:67], off
	global_load_dwordx4 v[114:117], v[80:81], off offset:256
	v_add_u32_e32 v66, 0x90, v172
	v_ashrrev_i32_e32 v67, 31, v66
	v_mad_i64_i32 v[68:69], s[0:1], v66, s43, v[174:175]
	v_lshl_add_u64 v[68:69], v[68:69], 0, s[20:21]
	v_lshlrev_b64 v[136:137], 11, v[66:67]
	v_lshl_add_u64 v[66:67], s[12:13], 0, v[136:137]
	v_lshl_add_u64 v[70:71], v[68:69], 0, v[170:171]
	v_lshl_add_u64 v[66:67], v[66:67], 0, v[170:171]
	global_load_dwordx4 v[118:121], v[70:71], off
	global_load_dwordx4 v[122:125], v[66:67], off
	v_lshl_add_u64 v[68:69], v[68:69], 0, v[176:177]
	global_load_dwordx4 v[126:129], v[68:69], off
	global_load_dwordx4 v[130:133], v[66:67], off offset:256
	v_add_u32_e32 v66, 0xa0, v172
	v_ashrrev_i32_e32 v67, 31, v66
	v_mad_i64_i32 v[68:69], s[0:1], v66, s43, v[174:175]
	v_lshl_add_u64 v[68:69], v[68:69], 0, s[20:21]
	v_lshlrev_b64 v[100:101], 11, v[66:67]
	v_lshl_add_u64 v[66:67], s[12:13], 0, v[100:101]
	v_lshl_add_u64 v[70:71], v[68:69], 0, v[170:171]
	v_lshl_add_u64 v[66:67], v[66:67], 0, v[170:171]
	global_load_dwordx4 v[94:97], v[70:71], off
	global_load_dwordx4 v[90:93], v[66:67], off
	v_lshl_add_u64 v[68:69], v[68:69], 0, v[176:177]
	global_load_dwordx4 v[86:89], v[68:69], off
	global_load_dwordx4 v[82:85], v[66:67], off offset:256
	v_add_u32_e32 v66, 0xb0, v172
	v_ashrrev_i32_e32 v67, 31, v66
	v_mad_i64_i32 v[68:69], s[0:1], v66, s43, v[174:175]
	v_lshl_add_u64 v[68:69], v[68:69], 0, s[20:21]
	v_lshlrev_b64 v[98:99], 11, v[66:67]
	v_lshl_add_u64 v[66:67], s[12:13], 0, v[98:99]
	v_lshl_add_u64 v[70:71], v[68:69], 0, v[170:171]
	v_lshl_add_u64 v[66:67], v[66:67], 0, v[170:171]
	global_load_dwordx4 v[78:81], v[70:71], off
	global_load_dwordx4 v[74:77], v[66:67], off
	v_lshl_add_u64 v[68:69], v[68:69], 0, v[176:177]
	global_load_dwordx4 v[70:73], v[68:69], off
	s_nop 0
	global_load_dwordx4 v[66:69], v[66:67], off offset:256
	v_and_b32_e32 v139, 0xffff0000, v102
	v_lshlrev_b32_e32 v102, 16, v103
	v_and_b32_e32 v103, 0xffff0000, v103
	v_lshlrev_b32_e32 v140, 16, v104
	v_and_b32_e32 v141, 0xffff0000, v104
	v_lshlrev_b32_e32 v104, 16, v105
	v_and_b32_e32 v105, 0xffff0000, v105
	s_waitcnt vmcnt(15)
	v_lshlrev_b32_e32 v142, 16, v106
	v_and_b32_e32 v143, 0xffff0000, v106
	v_lshlrev_b32_e32 v106, 16, v107
	v_and_b32_e32 v107, 0xffff0000, v107
	v_lshlrev_b32_e32 v144, 16, v108
	v_and_b32_e32 v145, 0xffff0000, v108
	v_lshlrev_b32_e32 v108, 16, v109
	v_and_b32_e32 v109, 0xffff0000, v109
	v_pk_fma_f32 v[64:65], v[64:65], v[102:103], v[106:107]
	v_pk_fma_f32 v[62:63], v[62:63], v[138:139], v[142:143]
	v_pk_fma_f32 v[102:103], v[60:61], v[104:105], v[108:109]
	v_pk_fma_f32 v[60:61], v[58:59], v[140:141], v[144:145]
	v_cvt_pk_bf16_f32 v58, v62, v63
	v_cvt_pk_bf16_f32 v59, v64, v65
	s_waitcnt vmcnt(13)
	v_lshlrev_b32_e32 v62, 16, v112
	v_cvt_pk_bf16_f32 v60, v60, v61
	v_cvt_pk_bf16_f32 v61, v102, v103
	global_store_dwordx4 v[134:135], v[58:61], off
	v_and_b32_e32 v63, 0xffff0000, v112
	v_lshlrev_b32_e32 v64, 16, v113
	v_lshlrev_b32_e32 v58, 16, v110
	v_and_b32_e32 v59, 0xffff0000, v110
	v_and_b32_e32 v65, 0xffff0000, v113
	s_waitcnt vmcnt(13)
	v_lshlrev_b32_e32 v102, 16, v114
	v_and_b32_e32 v103, 0xffff0000, v114
	v_lshlrev_b32_e32 v106, 16, v116
	v_and_b32_e32 v107, 0xffff0000, v116
	v_lshlrev_b32_e32 v108, 16, v117
	v_and_b32_e32 v109, 0xffff0000, v117
	v_lshlrev_b32_e32 v60, 16, v111
	v_and_b32_e32 v61, 0xffff0000, v111
	v_lshlrev_b32_e32 v104, 16, v115
	v_and_b32_e32 v105, 0xffff0000, v115
	v_pk_fma_f32 v[54:55], v[54:55], v[58:59], v[102:103]
	v_pk_fma_f32 v[58:59], v[52:53], v[64:65], v[108:109]
	v_pk_fma_f32 v[52:53], v[50:51], v[62:63], v[106:107]
	v_pk_fma_f32 v[56:57], v[56:57], v[60:61], v[104:105]
	v_cvt_pk_bf16_f32 v50, v54, v55
	v_cvt_pk_bf16_f32 v52, v52, v53
	v_cvt_pk_bf16_f32 v53, v58, v59
	s_waitcnt vmcnt(12)
	v_lshlrev_b32_e32 v54, 16, v120
	v_cvt_pk_bf16_f32 v51, v56, v57
	global_store_dwordx4 v[134:135], v[50:53], off offset:256
	v_and_b32_e32 v55, 0xffff0000, v120
	v_lshlrev_b32_e32 v56, 16, v121
	v_lshlrev_b32_e32 v50, 16, v118
	v_and_b32_e32 v51, 0xffff0000, v118
	v_lshlrev_b32_e32 v52, 16, v119
	v_and_b32_e32 v53, 0xffff0000, v119
	v_and_b32_e32 v57, 0xffff0000, v121
	s_waitcnt vmcnt(12)
	v_lshlrev_b32_e32 v58, 16, v122
	v_and_b32_e32 v59, 0xffff0000, v122
	v_lshlrev_b32_e32 v60, 16, v123
	v_and_b32_e32 v61, 0xffff0000, v123
	v_lshlrev_b32_e32 v62, 16, v124
	v_and_b32_e32 v63, 0xffff0000, v124
	v_lshlrev_b32_e32 v64, 16, v125
	v_and_b32_e32 v65, 0xffff0000, v125
	v_lshl_add_u64 v[102:103], s[14:15], 0, v[136:137]
	v_lshl_add_u64 v[102:103], v[102:103], 0, v[170:171]
	v_pk_fma_f32 v[48:49], v[48:49], v[52:53], v[60:61]
	v_pk_fma_f32 v[46:47], v[46:47], v[50:51], v[58:59]
	v_pk_fma_f32 v[50:51], v[44:45], v[56:57], v[64:65]
	v_pk_fma_f32 v[44:45], v[42:43], v[54:55], v[62:63]
	v_cvt_pk_bf16_f32 v42, v46, v47
	v_cvt_pk_bf16_f32 v43, v48, v49
	s_waitcnt vmcnt(11)
	v_lshlrev_b32_e32 v46, 16, v128
	v_cvt_pk_bf16_f32 v44, v44, v45
	v_cvt_pk_bf16_f32 v45, v50, v51
	global_store_dwordx4 v[102:103], v[42:45], off
	v_and_b32_e32 v47, 0xffff0000, v128
	v_lshlrev_b32_e32 v48, 16, v129
	v_lshlrev_b32_e32 v42, 16, v126
	v_and_b32_e32 v43, 0xffff0000, v126
	v_and_b32_e32 v49, 0xffff0000, v129
	s_waitcnt vmcnt(11)
	v_lshlrev_b32_e32 v50, 16, v130
	v_and_b32_e32 v51, 0xffff0000, v130
	v_lshlrev_b32_e32 v54, 16, v132
	v_and_b32_e32 v55, 0xffff0000, v132
	v_lshlrev_b32_e32 v56, 16, v133
	v_and_b32_e32 v57, 0xffff0000, v133
	v_lshlrev_b32_e32 v44, 16, v127
	v_and_b32_e32 v45, 0xffff0000, v127
	v_lshlrev_b32_e32 v52, 16, v131
	v_and_b32_e32 v53, 0xffff0000, v131
	v_pk_fma_f32 v[38:39], v[38:39], v[42:43], v[50:51]
	v_pk_fma_f32 v[42:43], v[36:37], v[48:49], v[56:57]
	v_pk_fma_f32 v[36:37], v[34:35], v[46:47], v[54:55]
	v_pk_fma_f32 v[40:41], v[40:41], v[44:45], v[52:53]
	v_cvt_pk_bf16_f32 v34, v38, v39
	v_cvt_pk_bf16_f32 v36, v36, v37
	v_cvt_pk_bf16_f32 v37, v42, v43
	s_waitcnt vmcnt(10)
	v_lshlrev_b32_e32 v38, 16, v96
	v_cvt_pk_bf16_f32 v35, v40, v41
	global_store_dwordx4 v[102:103], v[34:37], off offset:256
	v_and_b32_e32 v39, 0xffff0000, v96
	v_lshlrev_b32_e32 v40, 16, v97
	v_lshlrev_b32_e32 v34, 16, v94
	v_and_b32_e32 v35, 0xffff0000, v94
	v_lshlrev_b32_e32 v36, 16, v95
	v_and_b32_e32 v37, 0xffff0000, v95
	v_and_b32_e32 v41, 0xffff0000, v97
	s_waitcnt vmcnt(10)
	v_lshlrev_b32_e32 v42, 16, v90
	v_and_b32_e32 v43, 0xffff0000, v90
	v_lshlrev_b32_e32 v44, 16, v91
	v_and_b32_e32 v45, 0xffff0000, v91
	v_lshlrev_b32_e32 v46, 16, v92
	v_and_b32_e32 v47, 0xffff0000, v92
	v_lshlrev_b32_e32 v48, 16, v93
	v_and_b32_e32 v49, 0xffff0000, v93
	v_lshl_add_u64 v[50:51], s[14:15], 0, v[100:101]
	v_lshl_add_u64 v[50:51], v[50:51], 0, v[170:171]
	v_pk_fma_f32 v[32:33], v[32:33], v[36:37], v[44:45]
	v_pk_fma_f32 v[30:31], v[30:31], v[34:35], v[42:43]
	v_pk_fma_f32 v[34:35], v[28:29], v[40:41], v[48:49]
	v_pk_fma_f32 v[28:29], v[26:27], v[38:39], v[46:47]
	v_cvt_pk_bf16_f32 v26, v30, v31
	v_cvt_pk_bf16_f32 v27, v32, v33
	s_waitcnt vmcnt(9)
	v_lshlrev_b32_e32 v30, 16, v88
	v_cvt_pk_bf16_f32 v28, v28, v29
	v_cvt_pk_bf16_f32 v29, v34, v35
	global_store_dwordx4 v[50:51], v[26:29], off
	v_and_b32_e32 v31, 0xffff0000, v88
	v_lshlrev_b32_e32 v32, 16, v89
	v_lshlrev_b32_e32 v26, 16, v86
	v_and_b32_e32 v27, 0xffff0000, v86
	v_and_b32_e32 v33, 0xffff0000, v89
	s_waitcnt vmcnt(9)
	v_lshlrev_b32_e32 v34, 16, v82
	v_and_b32_e32 v35, 0xffff0000, v82
	v_lshlrev_b32_e32 v38, 16, v84
	v_and_b32_e32 v39, 0xffff0000, v84
	v_lshlrev_b32_e32 v40, 16, v85
	v_and_b32_e32 v41, 0xffff0000, v85
	v_lshlrev_b32_e32 v28, 16, v87
	v_and_b32_e32 v29, 0xffff0000, v87
	v_lshlrev_b32_e32 v36, 16, v83
	v_and_b32_e32 v37, 0xffff0000, v83
	v_pk_fma_f32 v[22:23], v[22:23], v[26:27], v[34:35]
	v_pk_fma_f32 v[26:27], v[20:21], v[32:33], v[40:41]
	v_pk_fma_f32 v[20:21], v[18:19], v[30:31], v[38:39]
	v_pk_fma_f32 v[24:25], v[24:25], v[28:29], v[36:37]
	v_cvt_pk_bf16_f32 v18, v22, v23
	v_cvt_pk_bf16_f32 v20, v20, v21
	v_cvt_pk_bf16_f32 v21, v26, v27
	s_waitcnt vmcnt(8)
	v_lshlrev_b32_e32 v22, 16, v80
	v_cvt_pk_bf16_f32 v19, v24, v25
	global_store_dwordx4 v[50:51], v[18:21], off offset:256
	v_and_b32_e32 v23, 0xffff0000, v80
	v_lshlrev_b32_e32 v24, 16, v81
	v_lshlrev_b32_e32 v18, 16, v78
	v_and_b32_e32 v19, 0xffff0000, v78
	v_lshlrev_b32_e32 v20, 16, v79
	v_and_b32_e32 v21, 0xffff0000, v79
	v_and_b32_e32 v25, 0xffff0000, v81
	s_waitcnt vmcnt(8)
	v_lshlrev_b32_e32 v26, 16, v74
	v_and_b32_e32 v27, 0xffff0000, v74
	v_lshlrev_b32_e32 v28, 16, v75
	v_and_b32_e32 v29, 0xffff0000, v75
	v_lshlrev_b32_e32 v30, 16, v76
	v_and_b32_e32 v31, 0xffff0000, v76
	v_lshlrev_b32_e32 v32, 16, v77
	v_and_b32_e32 v33, 0xffff0000, v77
	v_lshl_add_u64 v[34:35], s[14:15], 0, v[98:99]
	v_lshl_add_u64 v[34:35], v[34:35], 0, v[170:171]
	v_pk_fma_f32 v[16:17], v[16:17], v[20:21], v[28:29]
	v_pk_fma_f32 v[14:15], v[14:15], v[18:19], v[26:27]
	v_pk_fma_f32 v[18:19], v[12:13], v[24:25], v[32:33]
	v_pk_fma_f32 v[12:13], v[10:11], v[22:23], v[30:31]
	v_cvt_pk_bf16_f32 v10, v14, v15
	v_cvt_pk_bf16_f32 v11, v16, v17
	s_waitcnt vmcnt(7)
	v_lshlrev_b32_e32 v14, 16, v72
	v_cvt_pk_bf16_f32 v12, v12, v13
	v_cvt_pk_bf16_f32 v13, v18, v19
	global_store_dwordx4 v[34:35], v[10:13], off
	v_and_b32_e32 v15, 0xffff0000, v72
	v_lshlrev_b32_e32 v16, 16, v73
	v_lshlrev_b32_e32 v10, 16, v70
	v_and_b32_e32 v11, 0xffff0000, v70
	v_and_b32_e32 v17, 0xffff0000, v73
	s_waitcnt vmcnt(7)
	v_lshlrev_b32_e32 v18, 16, v66
	v_and_b32_e32 v19, 0xffff0000, v66
	v_lshlrev_b32_e32 v22, 16, v68
	v_and_b32_e32 v23, 0xffff0000, v68
	v_lshlrev_b32_e32 v24, 16, v69
	v_and_b32_e32 v25, 0xffff0000, v69
	v_lshlrev_b32_e32 v12, 16, v71
	v_and_b32_e32 v13, 0xffff0000, v71
	v_lshlrev_b32_e32 v20, 16, v67
	v_and_b32_e32 v21, 0xffff0000, v67
	v_pk_fma_f32 v[6:7], v[6:7], v[10:11], v[18:19]
	v_pk_fma_f32 v[10:11], v[4:5], v[16:17], v[24:25]
	v_pk_fma_f32 v[4:5], v[2:3], v[14:15], v[22:23]
	v_pk_fma_f32 v[8:9], v[8:9], v[12:13], v[20:21]
	v_cvt_pk_bf16_f32 v2, v6, v7
	v_cvt_pk_bf16_f32 v4, v4, v5
	v_cvt_pk_bf16_f32 v5, v10, v11
	s_nop 0
	v_cvt_pk_bf16_f32 v3, v8, v9
	global_store_dwordx4 v[34:35], v[2:5], off offset:256
.Lsplit8_epi:
	s_cbranch_vccnz .LBB0_1902
	s_andn2_b64 vcc, exec, s[10:11]
	s_cbranch_vccnz .LBB0_1901
	s_barrier
	s_branch .LBB0_1901
.LBB0_1914:
	s_waitcnt vmcnt(0)
	s_barrier
	s_cmp_gt_i32 s48, 32
	s_cbranch_scc0 .Ltr_skip8
	s_cmp_lt_u32 s2, 32
	s_cbranch_scc1 .Ltr_skip8
	s_sub_i32 s0, s2, 32
	v_lshl_add_u32 v92, s0, 3, v179
	v_add_u32_e32 v92, 0x200, v92
	s_movk_i32 s99, 0xcff
	s_mov_b32 s3, 32
	s_mov_b32 s98, 8
	s_branch .Ltr_late_entry

.LBB0_1982:
.LBB0_1983:
	s_cmp_lt_i32 s50, 10
	s_cselect_b64 s[0:1], -1, 0
	s_and_b64 s[8:9], s[0:1], s[4:5]
	s_andn2_b64 vcc, exec, s[8:9]
	s_cbranch_vccnz .LBB0_2018
	s_mov_b32 s101, 0
	v_readfirstlane_b32 s99, v179
	s_lshr_b32 s99, s99, 2
	s_cmpk_lt_i32 s2, 0x110
	s_cselect_b64 s[4:5], -1, 0
	s_add_i32 s0, 0, 0x20000
	v_mov_b32_e32 v2, s0
	s_barrier
	ds_read_b128 v[2:5], v2
	s_cmpk_gt_i32 s2, 0x10f
	v_readfirstlane_b32 s0, v178
	s_waitcnt lgkmcnt(0)
	v_readfirstlane_b32 s10, v2
	v_readfirstlane_b32 s11, v3
	v_readfirstlane_b32 s12, v4
	v_readfirstlane_b32 s13, v5
	s_cbranch_scc1 .LBB0_1986
	s_ashr_i32 s1, s2, 31
	s_lshr_b32 s1, s1, 29
	s_add_i32 s1, s2, s1
	s_ashr_i32 s3, s1, 3
	s_and_b32 s1, s1, -8
	s_sub_i32 s1, s2, s1
	s_cmp_lt_i32 s1, 0
	s_cselect_b32 s6, 35, 34
	s_mul_i32 s1, s1, s6
	s_add_i32 s1, s1, s3
	s_ashr_i32 s3, s1, 31
	s_lshr_b32 s3, s3, 27
	s_add_i32 s3, s1, s3
	s_ashr_i32 s3, s3, 5
	s_lshl_b32 s14, s3, 3
	s_sub_i32 s6, 0x44, s14
	s_lshl_b32 s3, s3, 5
	s_min_u32 s15, s6, 8
	s_sub_i32 s1, s1, s3
	s_sext_i32_i8 s3, s1
	v_cvt_f32_ubyte0_e32 v3, s15
	v_cvt_f32_i32_e32 v2, s3
	v_rcp_iflag_f32_e32 v4, v3
	s_ashr_i32 s3, s3, 30
	s_or_b32 s3, s3, 1
	v_mul_f32_e32 v4, v2, v4
	v_trunc_f32_e32 v4, v4
	v_fma_f32 v2, -v4, v3, v2
	v_cvt_i32_f32_e32 v4, v4
	v_cmp_ge_f32_e64 s[6:7], |v2|, v3
	s_and_b64 s[6:7], s[6:7], exec
	s_cselect_b32 s3, s3, 0
	v_readfirstlane_b32 s6, v4
	s_add_i32 s3, s6, s3
	s_sext_i32_i8 s34, s3
	s_mul_i32 s3, s3, s15
	s_sub_i32 s1, s1, s3
	s_sext_i32_i8 s1, s1
	s_add_i32 s36, s14, s1

.LBB0_1992:
	s_add_i32 s63, s63, 1
	s_mul_i32 s0, s63, s65
	s_mul_hi_u32 s1, s63, s69
	s_add_i32 s1, s1, s0
	s_mul_i32 s0, s63, s69
	s_add_u32 s28, s0, s2
	s_addc_u32 s29, s1, s66
	s_mov_b32 s100, s101
	s_mov_b32 s101, 0
	s_cmp_eq_u32 s48, 0x100
	s_cbranch_scc0 .Lsplit9_done
	s_cmp_eq_u32 s63, 1
	s_cbranch_scc0 .Lsplit9_done
	s_cmp_lt_u32 s2, 16
	s_cbranch_scc0 .Lsplit9_helper
	s_mov_b32 s101, 2
	s_branch .Lsplit9_done
.Lsplit9_helper:
	s_cmp_lt_u32 s2, 32
	s_cbranch_scc0 .Lsplit9_done
	s_sub_u32 s28, s28, 16
	s_mov_b32 s101, 1
.Lsplit9_done:
	s_sub_u32 s98, s100, 1
	v_cmp_gt_i64_e32 vcc, s[28:29], v[196:197]
	v_cmp_lt_i64_e64 s[6:7], s[28:29], v[194:195]
	s_cbranch_vccnz .LBB0_1994
	s_ashr_i32 s0, s28, 31
	s_lshr_b32 s0, s0, 29
	s_add_i32 s0, s28, s0
	s_ashr_i32 s1, s0, 3
	s_and_b32 s0, s0, -8
	s_sub_i32 s0, s28, s0
	s_cmp_lt_i32 s0, 0
	s_cselect_b32 s24, 35, 34
	s_mul_i32 s0, s0, s24
	s_add_i32 s0, s0, s1
	s_ashr_i32 s1, s0, 31
	s_lshr_b32 s1, s1, 27
	s_add_i32 s1, s0, s1
	s_ashr_i32 s24, s1, 5
	s_lshl_b32 s25, s24, 3
	s_sub_i32 s24, 0x44, s25
	s_min_i32 s26, s24, 8
	s_abs_i32 s24, s26
	v_cvt_f32_u32_e32 v2, s24
	s_sub_i32 s28, 0, s24
	s_andn2_b32 s1, s1, 31
	s_sub_i32 s0, s0, s1
	v_rcp_iflag_f32_e32 v2, v2
	s_abs_i32 s1, s0
	s_xor_b32 s27, s0, s26
	s_ashr_i32 s27, s27, 31
	v_mul_f32_e32 v2, 0x4f7ffffe, v2
	v_cvt_u32_f32_e32 v2, v2
	s_nop 0
	v_readfirstlane_b32 s29, v2
	s_mul_i32 s28, s28, s29
	s_mul_hi_u32 s28, s29, s28
	s_add_i32 s29, s29, s28
	s_mul_hi_u32 s28, s1, s29
	s_mul_i32 s29, s28, s24
	s_sub_i32 s1, s1, s29
	s_add_i32 s30, s28, 1
	s_sub_i32 s29, s1, s24
	s_cmp_ge_u32 s1, s24
	s_cselect_b32 s28, s30, s28
	s_cselect_b32 s1, s29, s1
	s_add_i32 s29, s28, 1
	s_cmp_ge_u32 s1, s24
	s_cselect_b32 s1, s29, s28
	s_xor_b32 s1, s1, s27
	s_sub_i32 s24, s1, s27
	s_mul_i32 s1, s24, s26
	s_sub_i32 s0, s0, s1
	s_add_i32 s26, s25, s0

.LBB0_1995:
	ds_read_b128 v[130:133], v213
	ds_read_b128 v[134:137], v213 offset:1024
	ds_read_b128 v[138:141], v213 offset:2048
	ds_read_b128 v[142:145], v213 offset:3072
	ds_read_b128 v[146:149], v214
	ds_read_b128 v[150:153], v214 offset:1024
	ds_read_b128 v[154:157], v214 offset:2048
	ds_read_b128 v[158:161], v214 offset:3072
	s_add_u32 s0, s38, 0xfffc0080
	s_addc_u32 s1, s39, -1
	s_cmp_eq_u32 s79, 12
	s_cselect_b32 s43, s27, s1
	s_cselect_b32 s42, s35, s0
	s_cselect_b32 s41, s25, s78
	s_cselect_b32 s40, s76, s77
	v_lshl_add_u64 v[222:223], s[38:39], 0, v[190:191]
	s_add_i32 m0, s37, 0xc000
	ds_read_b128 v[162:165], v215
	ds_read_b128 v[166:169], v215 offset:1024
	ds_read_b128 v[170:173], v215 offset:2048
	ds_read_b128 v[174:177], v215 offset:3072
	ds_read_b128 v[198:201], v215 offset:4096
	ds_read_b128 v[202:205], v215 offset:5120
	ds_read_b128 v[206:209], v215 offset:6144
	ds_read_b128 v[218:221], v215 offset:7168
	global_load_lds_dwordx4 v[222:223], off
	v_lshl_add_u64 v[222:223], s[38:39], 0, v[192:193]
	s_add_i32 m0, s37, 0xe000
	s_nop 0
	global_load_lds_dwordx4 v[222:223], off
	s_waitcnt vmcnt(8)
	s_waitcnt lgkmcnt(0)
	s_barrier
	s_cmp_eq_u32 s99, s98
	s_cbranch_scc1 .Lsplit9_mma0
	s_setprio 1
	s_waitcnt lgkmcnt(0)
	v_mfma_f32_16x16x32_bf16 v[126:129], v[130:133], v[162:165], v[126:129]
	v_mfma_f32_16x16x32_bf16 v[122:125], v[138:141], v[162:165], v[122:125]
	v_mfma_f32_16x16x32_bf16 v[110:113], v[130:133], v[170:173], v[110:113]
	v_mfma_f32_16x16x32_bf16 v[106:109], v[138:141], v[170:173], v[106:109]
	v_mfma_f32_16x16x32_bf16 v[94:97], v[130:133], v[198:201], v[94:97]
	v_mfma_f32_16x16x32_bf16 v[90:93], v[138:141], v[198:201], v[90:93]
	v_mfma_f32_16x16x32_bf16 v[78:81], v[130:133], v[206:209], v[78:81]
	v_mfma_f32_16x16x32_bf16 v[74:77], v[138:141], v[206:209], v[74:77]
	v_mfma_f32_16x16x32_bf16 v[126:129], v[134:137], v[166:169], v[126:129]
	v_mfma_f32_16x16x32_bf16 v[122:125], v[142:145], v[166:169], v[122:125]
	v_mfma_f32_16x16x32_bf16 v[110:113], v[134:137], v[174:177], v[110:113]
	v_mfma_f32_16x16x32_bf16 v[106:109], v[142:145], v[174:177], v[106:109]
	v_mfma_f32_16x16x32_bf16 v[94:97], v[134:137], v[202:205], v[94:97]
	v_mfma_f32_16x16x32_bf16 v[90:93], v[142:145], v[202:205], v[90:93]
	v_mfma_f32_16x16x32_bf16 v[78:81], v[134:137], v[218:221], v[78:81]
	v_mfma_f32_16x16x32_bf16 v[74:77], v[142:145], v[218:221], v[74:77]
	s_setprio 0
	s_setprio 1
	v_mfma_f32_16x16x32_bf16 v[118:121], v[146:149], v[162:165], v[118:121]
	v_mfma_f32_16x16x32_bf16 v[114:117], v[154:157], v[162:165], v[114:117]
	v_mfma_f32_16x16x32_bf16 v[102:105], v[146:149], v[170:173], v[102:105]
	v_mfma_f32_16x16x32_bf16 v[98:101], v[154:157], v[170:173], v[98:101]
	v_mfma_f32_16x16x32_bf16 v[86:89], v[146:149], v[198:201], v[86:89]
	v_mfma_f32_16x16x32_bf16 v[82:85], v[154:157], v[198:201], v[82:85]
	v_mfma_f32_16x16x32_bf16 v[70:73], v[146:149], v[206:209], v[70:73]
	v_mfma_f32_16x16x32_bf16 v[66:69], v[154:157], v[206:209], v[66:69]
	v_mfma_f32_16x16x32_bf16 v[118:121], v[150:153], v[166:169], v[118:121]
	v_mfma_f32_16x16x32_bf16 v[114:117], v[158:161], v[166:169], v[114:117]
	v_mfma_f32_16x16x32_bf16 v[102:105], v[150:153], v[174:177], v[102:105]
	v_mfma_f32_16x16x32_bf16 v[98:101], v[158:161], v[174:177], v[98:101]
	v_mfma_f32_16x16x32_bf16 v[86:89], v[150:153], v[202:205], v[86:89]
	v_mfma_f32_16x16x32_bf16 v[82:85], v[158:161], v[202:205], v[82:85]
	v_mfma_f32_16x16x32_bf16 v[70:73], v[150:153], v[218:221], v[70:73]
	v_mfma_f32_16x16x32_bf16 v[66:69], v[158:161], v[218:221], v[66:69]
	s_setprio 0
.Lsplit9_mma0:
	s_barrier
	s_add_i32 s0, s70, s59
	v_lshl_add_u64 v[222:223], s[40:41], 0, v[182:183]
	s_mov_b32 m0, s0
	ds_read_b128 v[162:165], v215 offset:16384
	ds_read_b128 v[166:169], v215 offset:17408
	ds_read_b128 v[170:173], v215 offset:18432
	ds_read_b128 v[174:177], v215 offset:19456
	ds_read_b128 v[198:201], v215 offset:20480
	ds_read_b128 v[202:205], v215 offset:21504
	ds_read_b128 v[206:209], v215 offset:22528
	ds_read_b128 v[218:221], v215 offset:23552
	global_load_lds_dwordx4 v[222:223], off
	s_add_i32 m0, s0, 0x2000
	s_add_u32 s0, s40, 0x40000
	v_lshl_add_u64 v[224:225], s[40:41], 0, v[186:187]
	s_addc_u32 s1, s41, 0
	s_add_i32 s33, s71, s59
	global_load_lds_dwordx4 v[224:225], off
	v_lshl_add_u64 v[226:227], s[0:1], 0, v[182:183]
	s_mov_b32 m0, s33
	v_lshl_add_u64 v[228:229], s[42:43], 0, v[184:185]
	global_load_lds_dwordx4 v[226:227], off
	v_lshl_add_u64 v[226:227], s[0:1], 0, v[186:187]
	s_add_i32 m0, s33, 0x2000
	s_nop 0
	global_load_lds_dwordx4 v[226:227], off
	v_lshl_add_u64 v[226:227], s[42:43], 0, v[180:181]
	s_mov_b32 m0, s37
	s_nop 0
	global_load_lds_dwordx4 v[226:227], off
	s_mov_b32 m0, s60
	s_nop 0
	global_load_lds_dwordx4 v[228:229], off
	s_waitcnt vmcnt(8)
	s_waitcnt lgkmcnt(0)
	s_barrier
	s_cmp_eq_u32 s99, s98
	s_cbranch_scc1 .Lsplit9_mma1
	s_setprio 1
	s_waitcnt lgkmcnt(0)
	v_mfma_f32_16x16x32_bf16 v[62:65], v[130:133], v[162:165], v[62:65]
	v_mfma_f32_16x16x32_bf16 v[58:61], v[138:141], v[162:165], v[58:61]
	v_mfma_f32_16x16x32_bf16 v[46:49], v[130:133], v[170:173], v[46:49]
	v_mfma_f32_16x16x32_bf16 v[42:45], v[138:141], v[170:173], v[42:45]
	v_mfma_f32_16x16x32_bf16 v[30:33], v[130:133], v[198:201], v[30:33]
	v_mfma_f32_16x16x32_bf16 v[26:29], v[138:141], v[198:201], v[26:29]
	v_mfma_f32_16x16x32_bf16 v[14:17], v[130:133], v[206:209], v[14:17]
	v_mfma_f32_16x16x32_bf16 v[10:13], v[138:141], v[206:209], v[10:13]
	v_mfma_f32_16x16x32_bf16 v[62:65], v[134:137], v[166:169], v[62:65]
	v_mfma_f32_16x16x32_bf16 v[58:61], v[142:145], v[166:169], v[58:61]
	v_mfma_f32_16x16x32_bf16 v[46:49], v[134:137], v[174:177], v[46:49]
	v_mfma_f32_16x16x32_bf16 v[42:45], v[142:145], v[174:177], v[42:45]
	v_mfma_f32_16x16x32_bf16 v[30:33], v[134:137], v[202:205], v[30:33]
	v_mfma_f32_16x16x32_bf16 v[26:29], v[142:145], v[202:205], v[26:29]
	v_mfma_f32_16x16x32_bf16 v[14:17], v[134:137], v[218:221], v[14:17]
	v_mfma_f32_16x16x32_bf16 v[10:13], v[142:145], v[218:221], v[10:13]
	s_setprio 0
	s_setprio 1
	v_mfma_f32_16x16x32_bf16 v[54:57], v[146:149], v[162:165], v[54:57]
	v_mfma_f32_16x16x32_bf16 v[50:53], v[154:157], v[162:165], v[50:53]
	v_mfma_f32_16x16x32_bf16 v[38:41], v[146:149], v[170:173], v[38:41]
	v_mfma_f32_16x16x32_bf16 v[34:37], v[154:157], v[170:173], v[34:37]
	v_mfma_f32_16x16x32_bf16 v[22:25], v[146:149], v[198:201], v[22:25]
	v_mfma_f32_16x16x32_bf16 v[18:21], v[154:157], v[198:201], v[18:21]
	v_mfma_f32_16x16x32_bf16 v[6:9], v[146:149], v[206:209], v[6:9]
	v_mfma_f32_16x16x32_bf16 v[2:5], v[154:157], v[206:209], v[2:5]
	v_mfma_f32_16x16x32_bf16 v[54:57], v[150:153], v[166:169], v[54:57]
	v_mfma_f32_16x16x32_bf16 v[50:53], v[158:161], v[166:169], v[50:53]
	v_mfma_f32_16x16x32_bf16 v[38:41], v[150:153], v[174:177], v[38:41]
	v_mfma_f32_16x16x32_bf16 v[34:37], v[158:161], v[174:177], v[34:37]
	v_mfma_f32_16x16x32_bf16 v[22:25], v[150:153], v[202:205], v[22:25]
	v_mfma_f32_16x16x32_bf16 v[18:21], v[158:161], v[202:205], v[18:21]
	v_mfma_f32_16x16x32_bf16 v[6:9], v[150:153], v[218:221], v[6:9]
	v_mfma_f32_16x16x32_bf16 v[2:5], v[158:161], v[218:221], v[2:5]
	s_setprio 0
.Lsplit9_mma1:
	s_barrier
	s_add_i32 s33, 0, 0x18000
	s_add_i32 s52, 0, 0x1c000
	v_add_u32_e32 v142, s33, v211
	v_add_u32_e32 v158, s52, v211
	ds_read_b128 v[130:133], v142
	ds_read_b128 v[134:137], v142 offset:1024
	ds_read_b128 v[138:141], v142 offset:2048
	ds_read_b128 v[142:145], v142 offset:3072
	ds_read_b128 v[146:149], v158
	ds_read_b128 v[150:153], v158 offset:1024
	ds_read_b128 v[154:157], v158 offset:2048
	ds_read_b128 v[158:161], v158 offset:3072
	s_add_u32 s0, s42, 0x40000
	s_addc_u32 s1, s43, 0
	s_mov_b32 m0, s61
	v_lshl_add_u64 v[230:231], s[0:1], 0, v[180:181]
	ds_read_b128 v[162:165], v215 offset:32768
	ds_read_b128 v[166:169], v215 offset:33792
	ds_read_b128 v[170:173], v215 offset:34816
	ds_read_b128 v[174:177], v215 offset:35840
	ds_read_b128 v[198:201], v215 offset:36864
	ds_read_b128 v[202:205], v215 offset:37888
	ds_read_b128 v[206:209], v215 offset:38912
	ds_read_b128 v[218:221], v215 offset:39936
	global_load_lds_dwordx4 v[230:231], off
	v_lshl_add_u64 v[230:231], s[0:1], 0, v[184:185]
	s_mov_b32 m0, s62
	s_nop 0
	global_load_lds_dwordx4 v[230:231], off
	s_waitcnt vmcnt(8)
	s_waitcnt lgkmcnt(0)
	s_barrier
	s_cmp_eq_u32 s99, s98
	s_cbranch_scc1 .Lsplit9_mma2
	s_setprio 1
	s_waitcnt lgkmcnt(0)
	v_mfma_f32_16x16x32_bf16 v[126:129], v[130:133], v[162:165], v[126:129]
	v_mfma_f32_16x16x32_bf16 v[122:125], v[138:141], v[162:165], v[122:125]
	v_mfma_f32_16x16x32_bf16 v[110:113], v[130:133], v[170:173], v[110:113]
	v_mfma_f32_16x16x32_bf16 v[106:109], v[138:141], v[170:173], v[106:109]
	v_mfma_f32_16x16x32_bf16 v[94:97], v[130:133], v[198:201], v[94:97]
	v_mfma_f32_16x16x32_bf16 v[90:93], v[138:141], v[198:201], v[90:93]
	v_mfma_f32_16x16x32_bf16 v[78:81], v[130:133], v[206:209], v[78:81]
	v_mfma_f32_16x16x32_bf16 v[74:77], v[138:141], v[206:209], v[74:77]
	v_mfma_f32_16x16x32_bf16 v[126:129], v[134:137], v[166:169], v[126:129]
	v_mfma_f32_16x16x32_bf16 v[122:125], v[142:145], v[166:169], v[122:125]
	v_mfma_f32_16x16x32_bf16 v[110:113], v[134:137], v[174:177], v[110:113]
	v_mfma_f32_16x16x32_bf16 v[106:109], v[142:145], v[174:177], v[106:109]
	v_mfma_f32_16x16x32_bf16 v[94:97], v[134:137], v[202:205], v[94:97]
	v_mfma_f32_16x16x32_bf16 v[90:93], v[142:145], v[202:205], v[90:93]
	v_mfma_f32_16x16x32_bf16 v[78:81], v[134:137], v[218:221], v[78:81]
	v_mfma_f32_16x16x32_bf16 v[74:77], v[142:145], v[218:221], v[74:77]
	s_setprio 0
	s_setprio 1
	v_mfma_f32_16x16x32_bf16 v[118:121], v[146:149], v[162:165], v[118:121]
	v_mfma_f32_16x16x32_bf16 v[114:117], v[154:157], v[162:165], v[114:117]
	v_mfma_f32_16x16x32_bf16 v[102:105], v[146:149], v[170:173], v[102:105]
	v_mfma_f32_16x16x32_bf16 v[98:101], v[154:157], v[170:173], v[98:101]
	v_mfma_f32_16x16x32_bf16 v[86:89], v[146:149], v[198:201], v[86:89]
	v_mfma_f32_16x16x32_bf16 v[82:85], v[154:157], v[198:201], v[82:85]
	v_mfma_f32_16x16x32_bf16 v[70:73], v[146:149], v[206:209], v[70:73]
	v_mfma_f32_16x16x32_bf16 v[66:69], v[154:157], v[206:209], v[66:69]
	v_mfma_f32_16x16x32_bf16 v[118:121], v[150:153], v[166:169], v[118:121]
	v_mfma_f32_16x16x32_bf16 v[114:117], v[158:161], v[166:169], v[114:117]
	v_mfma_f32_16x16x32_bf16 v[102:105], v[150:153], v[174:177], v[102:105]
	v_mfma_f32_16x16x32_bf16 v[98:101], v[158:161], v[174:177], v[98:101]
	v_mfma_f32_16x16x32_bf16 v[86:89], v[150:153], v[202:205], v[86:89]
	v_mfma_f32_16x16x32_bf16 v[82:85], v[158:161], v[202:205], v[82:85]
	v_mfma_f32_16x16x32_bf16 v[70:73], v[150:153], v[218:221], v[70:73]
	v_mfma_f32_16x16x32_bf16 v[66:69], v[158:161], v[218:221], v[66:69]
	s_setprio 0
.Lsplit9_mma2:
	s_barrier
	s_add_i32 s0, s33, s59
	v_lshl_add_u64 v[222:223], v[222:223], 0, s[20:21]
	s_mov_b32 m0, s0
	ds_read_b128 v[162:165], v215 offset:49152
	ds_read_b128 v[166:169], v215 offset:50176
	ds_read_b128 v[170:173], v215 offset:51200
	ds_read_b128 v[174:177], v215 offset:52224
	ds_read_b128 v[198:201], v215 offset:53248
	ds_read_b128 v[202:205], v215 offset:54272
	ds_read_b128 v[206:209], v215 offset:55296
	ds_read_b128 v[218:221], v215 offset:56320
	global_load_lds_dwordx4 v[222:223], off
	s_add_i32 m0, s0, 0x2000
	s_add_u32 s0, s40, 0x40080
	v_lshl_add_u64 v[222:223], v[224:225], 0, s[20:21]
	s_addc_u32 s1, s41, 0
	s_add_i32 s33, s52, s59
	global_load_lds_dwordx4 v[222:223], off
	v_lshl_add_u64 v[222:223], s[0:1], 0, v[182:183]
	s_mov_b32 m0, s33
	s_nop 0
	global_load_lds_dwordx4 v[222:223], off
	v_lshl_add_u64 v[222:223], s[0:1], 0, v[186:187]
	s_add_i32 m0, s33, 0x2000
	s_nop 0
	global_load_lds_dwordx4 v[222:223], off
	v_lshl_add_u64 v[222:223], v[226:227], 0, s[20:21]
	s_mov_b32 m0, s67
	s_nop 0
	global_load_lds_dwordx4 v[222:223], off
	v_lshl_add_u64 v[222:223], v[228:229], 0, s[20:21]
	s_mov_b32 m0, s68
	s_nop 0
	global_load_lds_dwordx4 v[222:223], off
	s_waitcnt vmcnt(8)
	s_waitcnt lgkmcnt(0)
	s_barrier
	s_cmp_eq_u32 s99, s98
	s_cbranch_scc1 .Lsplit9_mma3
	s_setprio 1
	s_waitcnt lgkmcnt(0)
	v_mfma_f32_16x16x32_bf16 v[62:65], v[130:133], v[162:165], v[62:65]
	v_mfma_f32_16x16x32_bf16 v[58:61], v[138:141], v[162:165], v[58:61]
	v_mfma_f32_16x16x32_bf16 v[46:49], v[130:133], v[170:173], v[46:49]
	v_mfma_f32_16x16x32_bf16 v[42:45], v[138:141], v[170:173], v[42:45]
	v_mfma_f32_16x16x32_bf16 v[30:33], v[130:133], v[198:201], v[30:33]
	v_mfma_f32_16x16x32_bf16 v[26:29], v[138:141], v[198:201], v[26:29]
	v_mfma_f32_16x16x32_bf16 v[14:17], v[130:133], v[206:209], v[14:17]
	v_mfma_f32_16x16x32_bf16 v[10:13], v[138:141], v[206:209], v[10:13]
	v_mfma_f32_16x16x32_bf16 v[62:65], v[134:137], v[166:169], v[62:65]
	v_mfma_f32_16x16x32_bf16 v[58:61], v[142:145], v[166:169], v[58:61]
	v_mfma_f32_16x16x32_bf16 v[46:49], v[134:137], v[174:177], v[46:49]
	v_mfma_f32_16x16x32_bf16 v[42:45], v[142:145], v[174:177], v[42:45]
	v_mfma_f32_16x16x32_bf16 v[30:33], v[134:137], v[202:205], v[30:33]
	v_mfma_f32_16x16x32_bf16 v[26:29], v[142:145], v[202:205], v[26:29]
	v_mfma_f32_16x16x32_bf16 v[14:17], v[134:137], v[218:221], v[14:17]
	v_mfma_f32_16x16x32_bf16 v[10:13], v[142:145], v[218:221], v[10:13]
	s_setprio 0
	s_setprio 1
	v_mfma_f32_16x16x32_bf16 v[54:57], v[146:149], v[162:165], v[54:57]
	v_mfma_f32_16x16x32_bf16 v[50:53], v[154:157], v[162:165], v[50:53]
	v_mfma_f32_16x16x32_bf16 v[38:41], v[146:149], v[170:173], v[38:41]
	v_mfma_f32_16x16x32_bf16 v[34:37], v[154:157], v[170:173], v[34:37]
	v_mfma_f32_16x16x32_bf16 v[22:25], v[146:149], v[198:201], v[22:25]
	v_mfma_f32_16x16x32_bf16 v[18:21], v[154:157], v[198:201], v[18:21]
	v_mfma_f32_16x16x32_bf16 v[6:9], v[146:149], v[206:209], v[6:9]
	v_mfma_f32_16x16x32_bf16 v[2:5], v[154:157], v[206:209], v[2:5]
	v_mfma_f32_16x16x32_bf16 v[54:57], v[150:153], v[166:169], v[54:57]
	v_mfma_f32_16x16x32_bf16 v[50:53], v[158:161], v[166:169], v[50:53]
	v_mfma_f32_16x16x32_bf16 v[38:41], v[150:153], v[174:177], v[38:41]
	v_mfma_f32_16x16x32_bf16 v[34:37], v[158:161], v[174:177], v[34:37]
	v_mfma_f32_16x16x32_bf16 v[22:25], v[150:153], v[202:205], v[22:25]
	v_mfma_f32_16x16x32_bf16 v[18:21], v[158:161], v[202:205], v[18:21]
	v_mfma_f32_16x16x32_bf16 v[6:9], v[150:153], v[218:221], v[6:9]
	v_mfma_f32_16x16x32_bf16 v[2:5], v[158:161], v[218:221], v[2:5]
	s_setprio 0
.Lsplit9_mma3:
	s_barrier
	s_add_i32 s79, s79, 2
	s_add_u32 s38, s38, 0x100
	s_addc_u32 s39, s39, 0
	s_add_u32 s77, s77, 0x100
	s_addc_u32 s78, s78, 0
	s_cmp_gt_u32 s79, 13
	s_cbranch_scc0 .LBB0_1995
	s_and_b64 vcc, exec, s[22:23]
	s_cbranch_vccz .LBB0_1998
	s_barrier
.LBB0_1998:
	s_cmp_eq_u32 s99, s98
	s_cbranch_scc1 .Lsplit9_epi
	v_lshl_add_u32 v200, s36, 8, v210
	v_add_u32_e32 v188, 0xffffc000, v200
	v_ashrrev_i32_e32 v201, 31, v200
	v_lshl_or_b32 v198, s34, 8, v212
	v_lshlrev_b64 v[130:131], 12, v[188:189]
	v_lshlrev_b64 v[132:133], 12, v[200:201]
	v_lshl_add_u64 v[130:131], s[12:13], 0, v[130:131]
	v_lshl_add_u64 v[132:133], s[10:11], 0, v[132:133]
	v_cmp_gt_i32_e32 vcc, s64, v200
	v_ashrrev_i32_e32 v199, 31, v198
	v_lshlrev_b64 v[202:203], 2, v[198:199]
	v_cndmask_b32_e32 v131, v131, v133, vcc
	v_cndmask_b32_e32 v130, v130, v132, vcc
	v_lshl_add_u64 v[130:131], v[130:131], 0, v[202:203]
	flat_load_dwordx4 v[218:221], v[130:131]
	flat_load_dwordx4 v[222:225], v[130:131] offset:16
	flat_load_dwordx4 v[226:229], v[130:131] offset:512
	flat_load_dwordx4 v[234:237], v[130:131] offset:528
	v_or_b32_e32 v208, 16, v200
	v_add_u32_e32 v188, 0xffffc010, v200
	v_ashrrev_i32_e32 v209, 31, v208
	v_lshlrev_b64 v[130:131], 12, v[188:189]
	v_lshlrev_b64 v[132:133], 12, v[208:209]
	v_lshl_add_u64 v[130:131], s[12:13], 0, v[130:131]
	v_lshl_add_u64 v[132:133], s[10:11], 0, v[132:133]
	v_cmp_gt_i32_e32 vcc, s64, v208
	v_or_b32_e32 v206, 32, v200
	v_add_u32_e32 v188, 0xffffc020, v200
	v_cndmask_b32_e32 v131, v131, v133, vcc
	v_cndmask_b32_e32 v130, v130, v132, vcc
	v_lshl_add_u64 v[130:131], v[130:131], 0, v[202:203]
	v_ashrrev_i32_e32 v207, 31, v206
	flat_load_dwordx4 v[174:177], v[130:131]
	flat_load_dwordx4 v[170:173], v[130:131] offset:16
	flat_load_dwordx4 v[166:169], v[130:131] offset:512
	flat_load_dwordx4 v[162:165], v[130:131] offset:528
	v_lshlrev_b64 v[130:131], 12, v[188:189]
	v_lshlrev_b64 v[132:133], 12, v[206:207]
	v_lshl_add_u64 v[130:131], s[12:13], 0, v[130:131]
	v_lshl_add_u64 v[132:133], s[10:11], 0, v[132:133]
	v_cmp_gt_i32_e32 vcc, s64, v206
	v_or_b32_e32 v204, 48, v200
	v_add_u32_e32 v188, 0xffffc030, v200
	v_cndmask_b32_e32 v131, v131, v133, vcc
	v_cndmask_b32_e32 v130, v130, v132, vcc
	v_lshl_add_u64 v[130:131], v[130:131], 0, v[202:203]
	v_ashrrev_i32_e32 v205, 31, v204
	flat_load_dwordx4 v[158:161], v[130:131]
	flat_load_dwordx4 v[154:157], v[130:131] offset:16
	flat_load_dwordx4 v[150:153], v[130:131] offset:512
	flat_load_dwordx4 v[146:149], v[130:131] offset:528
	v_lshlrev_b64 v[130:131], 12, v[188:189]
	v_lshlrev_b64 v[132:133], 12, v[204:205]
	v_lshl_add_u64 v[130:131], s[12:13], 0, v[130:131]
	v_lshl_add_u64 v[132:133], s[10:11], 0, v[132:133]
	v_cmp_gt_i32_e32 vcc, s64, v204
	v_lshlrev_b64 v[230:231], 11, v[200:201]
	v_lshl_add_u64 v[230:231], s[16:17], 0, v[230:231]
	v_cndmask_b32_e32 v131, v131, v133, vcc
	v_cndmask_b32_e32 v130, v130, v132, vcc
	v_lshl_add_u64 v[130:131], v[130:131], 0, v[202:203]
	flat_load_dwordx4 v[142:145], v[130:131]
	flat_load_dwordx4 v[138:141], v[130:131] offset:16
	flat_load_dwordx4 v[134:137], v[130:131] offset:512
	s_nop 0
	flat_load_dwordx4 v[130:133], v[130:131] offset:528
	v_lshl_add_u64 v[230:231], v[198:199], 1, v[230:231]
	s_waitcnt vmcnt(0) lgkmcnt(0)
	v_pk_add_f32 v[126:127], v[126:127], v[218:219]
	v_pk_add_f32 v[218:219], v[122:123], v[222:223]
	v_pk_add_f32 v[128:129], v[128:129], v[220:221]
	v_pk_add_f32 v[124:125], v[124:125], v[224:225]
	v_pk_add_f32 v[220:221], v[116:117], v[236:237]
	v_mul_f32_e32 v116, v218, v218
	v_mul_f32_e32 v117, v219, v219
	v_mul_f32_e32 v122, v124, v124
	v_fmac_f32_e32 v116, v126, v126
	v_fmac_f32_e32 v117, v127, v127
	v_pk_add_f32 v[222:223], v[114:115], v[234:235]
	v_mul_f32_e32 v123, v125, v125
	v_fmac_f32_e32 v122, v128, v128
	v_add_f32_e32 v116, v116, v117
	v_pk_add_f32 v[118:119], v[118:119], v[226:227]
	v_mul_f32_e32 v188, v222, v222
	v_fmac_f32_e32 v123, v129, v129
	v_add_f32_e32 v116, v122, v116
	v_mul_f32_e32 v217, v223, v223
	v_fmac_f32_e32 v188, v118, v118
	v_add_f32_e32 v116, v123, v116
	v_pk_add_f32 v[120:121], v[120:121], v[228:229]
	v_mul_f32_e32 v224, v220, v220
	v_fmac_f32_e32 v217, v119, v119
	v_add_f32_e32 v116, v188, v116
	v_add_f32_e32 v116, v217, v116
	v_fmac_f32_e32 v224, v120, v120
	v_mul_f32_e32 v117, v221, v221
	v_add_f32_e32 v116, v224, v116
	v_fmac_f32_e32 v117, v121, v121
	v_add_f32_e32 v123, v117, v116
	v_and_b32_e32 v117, 64, v216
	v_cvt_pk_bf16_f32 v114, v126, v127
	v_xor_b32_e32 v116, 16, v216
	v_add_u32_e32 v126, 64, v117
	v_cmp_lt_i32_e32 vcc, v116, v126
	v_cvt_pk_bf16_f32 v115, v128, v129
	v_cvt_pk_bf16_f32 v117, v124, v125
	s_nop 1
	v_cndmask_b32_e32 v116, v216, v116, vcc
	v_lshlrev_b32_e32 v122, 2, v116
	ds_bpermute_b32 v127, v122, v123
	v_cvt_pk_bf16_f32 v116, v218, v219
	global_store_dwordx4 v[230:231], v[114:117], off
	s_nop 1
	v_xor_b32_e32 v115, 32, v216
	v_cmp_lt_i32_e32 vcc, v115, v126
	s_waitcnt lgkmcnt(0)
	v_add_f32_e32 v114, v123, v127
	v_cvt_pk_bf16_f32 v116, v118, v119
	v_cvt_pk_bf16_f32 v117, v120, v121
	v_cvt_pk_bf16_f32 v118, v222, v223
	v_cvt_pk_bf16_f32 v119, v220, v221
	v_cndmask_b32_e32 v115, v216, v115, vcc
	v_lshlrev_b32_e32 v123, 2, v115
	ds_bpermute_b32 v115, v123, v114
	global_store_dwordx4 v[230:231], v[116:119], off offset:256
	s_and_saveexec_b64 s[34:35], s[4:5]
	s_cbranch_execz .LBB0_2000
	v_lshl_add_u64 v[116:117], v[200:201], 2, s[18:19]
	s_waitcnt lgkmcnt(0)
	v_add_f32_e32 v114, v114, v115
	global_atomic_add_f32 v[116:117], v114, off

.Lsplit9_epi:
	s_andn2_b64 vcc, exec, s[6:7]
	s_mov_b64 s[6:7], -1
	s_cbranch_vccnz .LBB0_1991
	s_andn2_b64 vcc, exec, s[14:15]
	s_cbranch_vccnz .LBB0_1990
	s_barrier
	s_branch .LBB0_1990
.LBB0_2017:
	s_waitcnt vmcnt(0)
	s_barrier
	s_cmp_gt_i32 s48, 32
	s_cbranch_scc0 .Ltr_skip9
	s_cmp_lt_u32 s2, 32
	s_cbranch_scc1 .Ltr_skip9
	s_sub_i32 s0, s2, 32
	v_lshl_add_u32 v92, s0, 3, v179
	v_add_u32_e32 v92, 0xd00, v92
	s_movk_i32 s99, 0x127f
	s_mov_b32 s3, 32
	s_mov_b32 s98, 9
	s_branch .Ltr_late_entry
